# v22
# baseline (speedup 1.0000x reference)
; __device__ __forceinline__ unsigned xb_ld(unsigned* p)              { return __hip_atomic_load(p, __ATOMIC_RELAXED, __HIP_MEMORY_SCOPE_AGENT); }
; __device__ __forceinline__ unsigned xb_add(unsigned* p, unsigned v) { return __hip_atomic_fetch_add(p, v, __ATOMIC_RELAXED, __HIP_MEMORY_SCOPE_AGENT); }
; #define XB_SPIN(cond, bar) do { unsigned _sp = 0; while (cond) { __builtin_amdgcn_s_sleep(1); \
;     if ((++_sp & 255u) == 0u) { if (xb_ld(&(bar)[XB_TMO])) break; if (_sp > XB_SPIN_CAP) { atomicAdd(&(bar)[XB_TMO], 1u); break; } } } } while (0)
; __device__ __forceinline__ void xcd_barrier(const XcdBarrier& b) {
;     ...
;         const unsigned old = xb_add(&bar[XB_XSUB(b.x)], 1u);
;         const unsigned gen = old / nloc;
;         if (old + 1u == (gen + 1u) * nloc) {
;             __builtin_amdgcn_fence(__ATOMIC_RELEASE, "agent");
;             asm volatile("s_waitcnt vmcnt(0)" ::: "memory");
;             const unsigned og = xb_add(&bar[XB_TOP], 1u);
;             const unsigned tg = og / nx;
;             if (og + 1u == (tg + 1u) * nx) xb_add(&bar[XB_TOPGEN], 1u);
;             else XB_SPIN(xb_ld(&bar[XB_TOPGEN]) == tg, bar);
;             __builtin_amdgcn_fence(__ATOMIC_ACQUIRE, "agent");
;             xb_add(&bar[XB_XGEN(b.x)], 1u);
;             asm volatile("s_waitcnt vmcnt(0)" ::: "memory");
;         } else {
;             XB_SPIN(xb_ld(&bar[XB_XGEN(b.x)]) == gen, bar);
;             __builtin_amdgcn_fence(__ATOMIC_ACQUIRE, "agent");
;             asm volatile("s_waitcnt vmcnt(0)" ::: "memory");
;         }
.Llb_go_10:
	s_add_u32 s22, s14, 0x25d06100
	s_addc_u32 s23, s15, 0
	v_mov_b32_e32 v2, 0
	v_mov_b32_e32 v3, 1
	global_atomic_add v2, v3, s[22:23]
	s_mov_b32 s24, 0
.Llb_gw_10:
	s_sleep 1
	global_load_dword v4, v2, s[22:23] sc1
	s_waitcnt vmcnt(0)
	v_readfirstlane_b32 s25, v4
	s_cmp_ge_u32 s25, 256
	s_cbranch_scc1 .Llb_acq_10
	s_add_u32 s24, s24, 1
	s_cmp_lt_u32 s24, 0x100000
	s_cbranch_scc1 .Llb_gw_10
	s_branch .Llb_acq_10
	s_and_b32 s16, s2, 7
	s_lshl_b32 s16, s16, 8
	s_add_u32 s20, s14, 0x25d05000
	s_addc_u32 s21, s15, 0
	s_add_u32 s20, s20, s16
	s_addc_u32 s21, s21, 0
	v_mov_b32_e32 v2, 0
	v_mov_b32_e32 v3, 1
	global_atomic_add v4, v2, v3, s[20:21] sc0
	s_waitcnt vmcnt(0)
	v_readfirstlane_b32 s17, v4
	s_lshr_b32 s22, s17, 5
	s_add_u32 s17, s17, 1
	s_and_b32 s17, s17, 31
	s_cmp_eq_u32 s17, 0
	s_cbranch_scc0 .Llb_wait_10
	global_atomic_add v2, v3, s[20:21] offset:2048
	s_branch .Llb_acq_10

; __device__ __forceinline__ unsigned xb_add(unsigned* p, unsigned v) { return __hip_atomic_fetch_add(p, v, __ATOMIC_RELAXED, __HIP_MEMORY_SCOPE_AGENT); }
; __device__ __forceinline__ void xcd_barrier(const XcdBarrier& b) {
;     asm volatile("s_waitcnt vmcnt(0)" ::: "memory");
;     __syncthreads();
;     if (threadIdx.x == 0) {
;         unsigned* bar = b.bar;
;         __builtin_amdgcn_s_waitcnt(0);
;         unsigned nloc = b.st[0], nx = b.st[1];
;         if (nloc == 0u) { xcd_barrier_complete(bar, b.x, nloc, nx); b.st[0] = nloc; b.st[1] = nx; }
;         const unsigned old = xb_add(&bar[XB_XSUB(b.x)], 1u);
.LBB0_2392:
	s_getreg_b32 s6, hwreg(HW_REG_XCC_ID, 0, 4)
	s_waitcnt vmcnt(0)
	s_waitcnt lgkmcnt(0)
	s_barrier
	s_and_saveexec_b64 s[2:3], s[4:5]
	s_cbranch_execz .LBB0_2444
	v_writelane_b32 v16, s14, 0
	v_writelane_b32 v16, s15, 1
	v_writelane_b32 v16, s16, 2
	v_writelane_b32 v16, s17, 3
	v_writelane_b32 v16, s18, 4
	v_writelane_b32 v16, s19, 5
	v_writelane_b32 v16, s20, 6
	v_writelane_b32 v16, s21, 7
	v_writelane_b32 v16, s22, 8
	v_writelane_b32 v16, s23, 9
	v_writelane_b32 v16, s24, 10
	v_writelane_b32 v16, s25, 11
	v_mov_b32_e32 v10, 0x23f08
	ds_read_b32 v11, v10
	s_load_dwordx2 s[14:15], s[0:1], 0xc0
	s_waitcnt lgkmcnt(0)
	v_readfirstlane_b32 s16, v11
	s_cmp_eq_u32 s16, 1
	s_cbranch_scc1 .Llb_go_19
	s_cmp_eq_u32 s16, 2
	s_cbranch_scc1 .Llb_full_19
	s_mov_b64 s[18:19], exec
	s_mov_b64 exec, -1
	s_add_u32 s20, s14, 0x25d04000
	s_addc_u32 s21, s15, 0
	v_and_b32_e32 v2, 63, v234
	v_lshlrev_b32_e32 v3, 2, v2
	v_and_b32_e32 v9, 7, v2
	v_lshlrev_b32_e32 v9, 2, v9
	global_load_dword v4, v3, s[20:21] sc1
	global_load_dword v5, v3, s[20:21] offset:256 sc1
	global_load_dword v6, v3, s[20:21] offset:512 sc1
	global_load_dword v7, v3, s[20:21] offset:768 sc1
	global_load_dword v8, v9, s[20:21] sc1
	s_waitcnt vmcnt(0)
	v_cmp_eq_u32_e32 vcc, v4, v8
	s_mov_b64 s[24:25], vcc
	v_cmp_eq_u32_e32 vcc, v5, v8
	s_and_b64 s[24:25], s[24:25], vcc
	v_cmp_eq_u32_e32 vcc, v6, v8
	s_and_b64 s[24:25], s[24:25], vcc
	v_cmp_eq_u32_e32 vcc, v7, v8
	s_and_b64 s[24:25], s[24:25], vcc
	v_cmp_ne_u32_e32 vcc, 0, v8
	s_and_b64 s[24:25], s[24:25], vcc
	s_mov_b32 s16, 2
	s_cmp_eq_u64 s[24:25], exec
	s_cbranch_scc0 .Llb_dec_19
	s_cmpk_eq_i32 s46, 0x100
	s_cbranch_scc0 .Llb_dec_19
	s_mov_b32 s16, 1

; __device__ __forceinline__ unsigned xb_add(unsigned* p, unsigned v) { return __hip_atomic_fetch_add(p, v, __ATOMIC_RELAXED, __HIP_MEMORY_SCOPE_AGENT); }
; __device__ __forceinline__ void xcd_barrier(const XcdBarrier& b) {
;     ...
;         const unsigned old = xb_add(&bar[XB_XSUB(b.x)], 1u);
;         const unsigned gen = old / nloc;
;         if (old + 1u == (gen + 1u) * nloc) {
;             __builtin_amdgcn_fence(__ATOMIC_RELEASE, "agent");
;             asm volatile("s_waitcnt vmcnt(0)" ::: "memory");
;             const unsigned og = xb_add(&bar[XB_TOP], 1u);
;             const unsigned tg = og / nx;
;             if (og + 1u == (tg + 1u) * nx) xb_add(&bar[XB_TOPGEN], 1u);
.Llb_go_19:
	s_add_u32 s22, s14, 0x25d06200
	s_addc_u32 s23, s15, 0
	v_mov_b32_e32 v2, 0
	v_mov_b32_e32 v3, 1
	global_atomic_add v2, v3, s[22:23]
	s_mov_b32 s24, 0

; __device__ __forceinline__ unsigned xb_ld(unsigned* p)              { return __hip_atomic_load(p, __ATOMIC_RELAXED, __HIP_MEMORY_SCOPE_AGENT); }
; __device__ __forceinline__ void xcd_barrier_complete(unsigned* bar, unsigned x, unsigned& nloc, unsigned& nx) {
;     const unsigned G = gridDim.x * gridDim.y * gridDim.z;
;     unsigned sum, cnt, mine, sp = 0u;
;     for (;;) {
;         sum = 0u; cnt = 0u; mine = 0u;
; #pragma unroll
;         for (unsigned j = 0; j < 16; ++j) { const unsigned c = xb_ld(&bar[XB_XCNT(j)]); sum += c; cnt += (c > 0u) ? 1u : 0u; mine = (j == x) ? c : mine; }
;         if (sum == G) break;
;         __builtin_amdgcn_s_sleep(1);
;         if ((++sp & 255u) == 0u) { if (xb_ld(&bar[XB_TMO])) break; if (sp > XB_SPIN_CAP) { atomicAdd(&bar[XB_TMO], 1u); break; } }
;     }
;     nloc = mine > 0u ? mine : 1u; nx = cnt > 0u ? cnt : 1u;
; }
; __device__ __forceinline__ void xcd_barrier(const XcdBarrier& b) {
;     asm volatile("s_waitcnt vmcnt(0)" ::: "memory");
;     __syncthreads();
;     if (threadIdx.x == 0) {
;         unsigned* bar = b.bar;
;         __builtin_amdgcn_s_waitcnt(0);
;         unsigned nloc = b.st[0], nx = b.st[1];
;         if (nloc == 0u) { xcd_barrier_complete(bar, b.x, nloc, nx); b.st[0] = nloc; b.st[1] = nx; }
.Llb_full_19:
	v_readlane_b32 s14, v16, 0
	v_readlane_b32 s15, v16, 1
	v_readlane_b32 s16, v16, 2
	v_readlane_b32 s17, v16, 3
	v_readlane_b32 s18, v16, 4
	v_readlane_b32 s19, v16, 5
	v_readlane_b32 s20, v16, 6
	v_readlane_b32 s21, v16, 7
	v_readlane_b32 s22, v16, 8
	v_readlane_b32 s23, v16, 9
	v_readlane_b32 s24, v16, 10
	v_readlane_b32 s25, v16, 11
	s_nop 4
	s_load_dwordx2 s[4:5], s[0:1], 0xc0
	s_ashr_i32 s11, s10, 31
	s_lshl_b64 s[8:9], s[10:11], 2
	s_waitcnt vmcnt(0) expcnt(0) lgkmcnt(0)
	s_add_u32 s4, s4, s8
	s_addc_u32 s5, s5, s9
	s_add_u32 s4, s4, 0x25d00000
	s_addc_u32 s5, s5, 0
	s_add_i32 s21, s10, 0
	s_add_i32 s21, s21, 0x23f00
	v_mov_b32_e32 v0, s21
	ds_read_b32 v2, v0
	ds_read_b32 v0, v0 offset:4
	s_and_b32 s20, s6, 15
	s_waitcnt lgkmcnt(1)
	v_cmp_ne_u32_e32 vcc, 0, v2
	s_cbranch_vccnz .LBB0_2408
	s_add_u32 s6, s4, 0x1000
	s_addc_u32 s7, s5, 0
	s_add_u32 s8, s4, 0x1100
	s_addc_u32 s9, s5, 0
	s_add_u32 s10, s4, 0x1200
	s_addc_u32 s11, s5, 0
	s_mul_i32 s22, s47, s94
	s_add_u32 s12, s4, 0x1300
	s_mul_i32 s22, s22, s46
	s_addc_u32 s13, s5, 0
	s_mov_b32 s23, 1
	v_mov_b32_e32 v16, 0
	s_branch .LBB0_2396

; __device__ __forceinline__ void final_norm_pass(const Ctx& C, const bf16* XB, const float* g, float* out) {
;     const int gw = C.bid * 8 + C.wave, NGW = C.G * 8;
;     for (int m = gw; m < M; m += NGW) {
;         const v2u* xr = (const v2u*)(XB + (size_t)m * D) + C.lane; f32x4 v[8]; float s = 0.f;
; #pragma unroll
;         for (int j = 0; j < 8; ++j) { const v2u w = xr[64 * j]; v[j] = (f32x4){__uint_as_float(w.x << 16), __uint_as_float(w.x & 0xffff0000u), __uint_as_float(w.y << 16), __uint_as_float(w.y & 0xffff0000u)};
;             s += (v[j][0] * v[j][0] + v[j][1] * v[j][1]) + (v[j][2] * v[j][2] + v[j][3] * v[j][3]); }
;         const float rstd = rsqrtf(wave_sum(s) * (1.0f / D) + EPS);
;         const f32x4* gr = (const f32x4*)g + C.lane; f32x4* o = (f32x4*)(out + (size_t)m * D) + C.lane;
; #pragma unroll
;         for (int j = 0; j < 8; ++j) o[64 * j] = v[j] * rstd * gr[64 * j];
;     }
; __global__ void __launch_bounds__(NTHR, 2) fwd_megakernel(Args args) {
;     ...
;     { constexpr int li = 0; MKCTX(); final_norm_pass(C, XP, C.in[22], C.X); }
.LBB0_2444:
	s_or_b64 exec, exec, s[2:3]
	s_waitcnt lgkmcnt(0)
	s_barrier
	v_readlane_b32 s3, v254, 0
	v_readfirstlane_b32 s2, v234
	s_ashr_i32 s2, s2, 6
	s_lshr_b32 s8, s3, 3
	s_and_b32 s8, s8, 7
	s_lshl_b32 s8, s8, 11
	s_add_u32 s2, s2, s8
	s_lshr_b32 s8, s3, 6
	s_lshl_b32 s8, s8, 3
	s_add_u32 s2, s2, s8
	s_mov_b32 s8, 0
	s_cmpk_gt_i32 s2, 0x3fff
	s_cbranch_scc1 .LBB0_2447
	s_load_dwordx2 s[12:13], s[0:1], 0xb0
	s_load_dwordx4 s[4:7], s[0:1], 0xb8
	v_and_b32_e32 v1, 63, v234
	v_lshlrev_b32_e32 v2, 4, v1
	v_lshlrev_b32_e32 v3, 3, v1
	v_lshlrev_b32_e32 v4, 2, v1
	v_xor_b32_e32 v10, 4, v4
	v_xor_b32_e32 v11, 8, v4
	v_xor_b32_e32 v12, 16, v4
	v_xor_b32_e32 v13, 32, v4
	v_xor_b32_e32 v14, 64, v4
	v_xor_b32_e32 v15, 128, v4
	v_mov_b32_e32 v5, 0x358637bd
	s_waitcnt lgkmcnt(0)
	s_add_u32 s12, s12, 0x1000
	s_addc_u32 s13, s13, 0
	global_load_dwordx4 v[128:131], v2, s[12:13] offset:-4096
	global_load_dwordx4 v[132:135], v2, s[12:13] offset:-3072
	global_load_dwordx4 v[136:139], v2, s[12:13] offset:-2048
	global_load_dwordx4 v[140:143], v2, s[12:13] offset:-1024
	global_load_dwordx4 v[144:147], v2, s[12:13] offset:0
	global_load_dwordx4 v[148:151], v2, s[12:13] offset:1024
	global_load_dwordx4 v[152:155], v2, s[12:13] offset:2048
	global_load_dwordx4 v[156:159], v2, s[12:13] offset:3072
	s_add_u32 s6, s6, 0x26100800
	s_addc_u32 s7, s7, 0
	s_add_u32 s4, s4, 0x1000
	s_addc_u32 s5, s5, 0
	s_lshl_b32 s8, s2, 12
	s_add_u32 s10, s6, s8
	s_addc_u32 s11, s7, 0
	global_load_dwordx2 v[20:21], v3, s[10:11] offset:-2048
	global_load_dwordx2 v[22:23], v3, s[10:11] offset:-1536
	global_load_dwordx2 v[24:25], v3, s[10:11] offset:-1024
	global_load_dwordx2 v[26:27], v3, s[10:11] offset:-512
	global_load_dwordx2 v[28:29], v3, s[10:11] offset:0
	global_load_dwordx2 v[30:31], v3, s[10:11] offset:512
	global_load_dwordx2 v[32:33], v3, s[10:11] offset:1024
	global_load_dwordx2 v[34:35], v3, s[10:11] offset:1536
	s_lshl_b32 s8, s2, 13
	s_add_u32 s14, s4, s8
	s_addc_u32 s15, s5, 0
	s_addk_i32 s2, 0x100
	s_lshl_b32 s8, s2, 12
	s_add_u32 s10, s6, s8
	s_addc_u32 s11, s7, 0
	global_load_dwordx2 v[36:37], v3, s[10:11] offset:-2048
	global_load_dwordx2 v[38:39], v3, s[10:11] offset:-1536
	global_load_dwordx2 v[40:41], v3, s[10:11] offset:-1024
	global_load_dwordx2 v[42:43], v3, s[10:11] offset:-512
	global_load_dwordx2 v[44:45], v3, s[10:11] offset:0
	global_load_dwordx2 v[46:47], v3, s[10:11] offset:512
	global_load_dwordx2 v[48:49], v3, s[10:11] offset:1024
	global_load_dwordx2 v[50:51], v3, s[10:11] offset:1536
	s_waitcnt vmcnt(8)
	v_lshlrev_b32_e32 v64, 16, v20
	v_and_b32_e32 v65, 0xffff0000, v20
	v_lshlrev_b32_e32 v66, 16, v21
	v_and_b32_e32 v67, 0xffff0000, v21
	v_mul_f32_e32 v8, v65, v65
	v_mul_f32_e32 v9, v67, v67
	v_fmac_f32_e32 v8, v64, v64
	v_fmac_f32_e32 v9, v66, v66
	v_add_f32_e32 v17, v8, v9
	v_lshlrev_b32_e32 v68, 16, v22
	v_and_b32_e32 v69, 0xffff0000, v22
	v_lshlrev_b32_e32 v70, 16, v23
	v_and_b32_e32 v71, 0xffff0000, v23
	v_mul_f32_e32 v8, v69, v69
	v_mul_f32_e32 v9, v71, v71
	v_fmac_f32_e32 v8, v68, v68
	v_fmac_f32_e32 v9, v70, v70
	v_add_f32_e32 v8, v8, v9
	v_add_f32_e32 v17, v17, v8
	v_lshlrev_b32_e32 v72, 16, v24
	v_and_b32_e32 v73, 0xffff0000, v24
	v_lshlrev_b32_e32 v74, 16, v25
	v_and_b32_e32 v75, 0xffff0000, v25
	v_mul_f32_e32 v8, v73, v73
	v_mul_f32_e32 v9, v75, v75
	v_fmac_f32_e32 v8, v72, v72
	v_fmac_f32_e32 v9, v74, v74
	v_add_f32_e32 v8, v8, v9
	v_add_f32_e32 v17, v17, v8
	v_lshlrev_b32_e32 v76, 16, v26
	v_and_b32_e32 v77, 0xffff0000, v26
	v_lshlrev_b32_e32 v78, 16, v27
	v_and_b32_e32 v79, 0xffff0000, v27
	v_mul_f32_e32 v8, v77, v77
	v_mul_f32_e32 v9, v79, v79
	v_fmac_f32_e32 v8, v76, v76
	v_fmac_f32_e32 v9, v78, v78
	v_add_f32_e32 v8, v8, v9
	v_add_f32_e32 v17, v17, v8
	v_lshlrev_b32_e32 v80, 16, v28
	v_and_b32_e32 v81, 0xffff0000, v28
	v_lshlrev_b32_e32 v82, 16, v29
	v_and_b32_e32 v83, 0xffff0000, v29
	v_mul_f32_e32 v8, v81, v81
	v_mul_f32_e32 v9, v83, v83
	v_fmac_f32_e32 v8, v80, v80
	v_fmac_f32_e32 v9, v82, v82
	v_add_f32_e32 v8, v8, v9
	v_add_f32_e32 v17, v17, v8
	v_lshlrev_b32_e32 v84, 16, v30
	v_and_b32_e32 v85, 0xffff0000, v30
	v_lshlrev_b32_e32 v86, 16, v31
	v_and_b32_e32 v87, 0xffff0000, v31
	v_mul_f32_e32 v8, v85, v85
	v_mul_f32_e32 v9, v87, v87
	v_fmac_f32_e32 v8, v84, v84
	v_fmac_f32_e32 v9, v86, v86
	v_add_f32_e32 v8, v8, v9
	v_add_f32_e32 v17, v17, v8
	v_lshlrev_b32_e32 v88, 16, v32
	v_and_b32_e32 v89, 0xffff0000, v32
	v_lshlrev_b32_e32 v90, 16, v33
	v_and_b32_e32 v91, 0xffff0000, v33
	v_mul_f32_e32 v8, v89, v89
	v_mul_f32_e32 v9, v91, v91
	v_fmac_f32_e32 v8, v88, v88
	v_fmac_f32_e32 v9, v90, v90
	v_add_f32_e32 v8, v8, v9
	v_add_f32_e32 v17, v17, v8
	v_lshlrev_b32_e32 v92, 16, v34
	v_and_b32_e32 v93, 0xffff0000, v34
	v_lshlrev_b32_e32 v94, 16, v35
	v_and_b32_e32 v95, 0xffff0000, v35
	v_mul_f32_e32 v8, v93, v93
	v_mul_f32_e32 v9, v95, v95
	v_fmac_f32_e32 v8, v92, v92
	v_fmac_f32_e32 v9, v94, v94
	v_add_f32_e32 v8, v8, v9
	v_add_f32_e32 v17, v17, v8
	ds_bpermute_b32 v18, v10, v17
	s_waitcnt lgkmcnt(0)
	v_add_f32_e32 v17, v17, v18
	ds_bpermute_b32 v18, v11, v17
	s_waitcnt lgkmcnt(0)
	v_add_f32_e32 v17, v17, v18
	ds_bpermute_b32 v18, v12, v17
	s_waitcnt lgkmcnt(0)
	v_add_f32_e32 v17, v17, v18
	ds_bpermute_b32 v18, v13, v17
	s_waitcnt lgkmcnt(0)
	v_add_f32_e32 v17, v17, v18
	ds_bpermute_b32 v18, v14, v17
	s_waitcnt lgkmcnt(0)
	v_add_f32_e32 v17, v17, v18
	ds_bpermute_b32 v18, v15, v17
	s_waitcnt lgkmcnt(0)
; __device__ __forceinline__ void final_norm_pass(const Ctx& C, const bf16* XB, const float* g, float* out) {
;     ...
;     for (int m = gw; m < M; m += NGW) {
;         const v2u* xr = (const v2u*)(XB + (size_t)m * D) + C.lane; f32x4 v[8]; float s = 0.f;
; #pragma unroll
;         for (int j = 0; j < 8; ++j) { const v2u w = xr[64 * j]; v[j] = (f32x4){__uint_as_float(w.x << 16), __uint_as_float(w.x & 0xffff0000u), __uint_as_float(w.y << 16), __uint_as_float(w.y & 0xffff0000u)};
;             s += (v[j][0] * v[j][0] + v[j][1] * v[j][1]) + (v[j][2] * v[j][2] + v[j][3] * v[j][3]); }
;         const float rstd = rsqrtf(wave_sum(s) * (1.0f / D) + EPS);
;         const f32x4* gr = (const f32x4*)g + C.lane; f32x4* o = (f32x4*)(out + (size_t)m * D) + C.lane;
; #pragma unroll
;         for (int j = 0; j < 8; ++j) o[64 * j] = v[j] * rstd * gr[64 * j];
;     }
	v_add_f32_e32 v17, v17, v18
	v_fmamk_f32 v6, v17, 0x3a000000, v5
	v_rsq_f32_e32 v6, v6
	s_nop 0
	v_pk_mul_f32 v[64:65], v[6:7], v[64:65] op_sel_hi:[0,1]
	v_pk_mul_f32 v[66:67], v[6:7], v[66:67] op_sel_hi:[0,1]
	v_pk_mul_f32 v[96:97], v[128:129], v[64:65]
	v_pk_mul_f32 v[98:99], v[130:131], v[66:67]
	global_store_dwordx4 v2, v[96:99], s[14:15] offset:-4096
	v_pk_mul_f32 v[68:69], v[6:7], v[68:69] op_sel_hi:[0,1]
	v_pk_mul_f32 v[70:71], v[6:7], v[70:71] op_sel_hi:[0,1]
	v_pk_mul_f32 v[100:101], v[132:133], v[68:69]
	v_pk_mul_f32 v[102:103], v[134:135], v[70:71]
	global_store_dwordx4 v2, v[100:103], s[14:15] offset:-3072
	v_pk_mul_f32 v[72:73], v[6:7], v[72:73] op_sel_hi:[0,1]
	v_pk_mul_f32 v[74:75], v[6:7], v[74:75] op_sel_hi:[0,1]
	v_pk_mul_f32 v[104:105], v[136:137], v[72:73]
	v_pk_mul_f32 v[106:107], v[138:139], v[74:75]
	global_store_dwordx4 v2, v[104:107], s[14:15] offset:-2048
	v_pk_mul_f32 v[76:77], v[6:7], v[76:77] op_sel_hi:[0,1]
	v_pk_mul_f32 v[78:79], v[6:7], v[78:79] op_sel_hi:[0,1]
	v_pk_mul_f32 v[108:109], v[140:141], v[76:77]
	v_pk_mul_f32 v[110:111], v[142:143], v[78:79]
	global_store_dwordx4 v2, v[108:111], s[14:15] offset:-1024
	v_pk_mul_f32 v[80:81], v[6:7], v[80:81] op_sel_hi:[0,1]
	v_pk_mul_f32 v[82:83], v[6:7], v[82:83] op_sel_hi:[0,1]
	v_pk_mul_f32 v[112:113], v[144:145], v[80:81]
	v_pk_mul_f32 v[114:115], v[146:147], v[82:83]
	global_store_dwordx4 v2, v[112:115], s[14:15] offset:0
	v_pk_mul_f32 v[84:85], v[6:7], v[84:85] op_sel_hi:[0,1]
	v_pk_mul_f32 v[86:87], v[6:7], v[86:87] op_sel_hi:[0,1]
	v_pk_mul_f32 v[116:117], v[148:149], v[84:85]
	v_pk_mul_f32 v[118:119], v[150:151], v[86:87]
	global_store_dwordx4 v2, v[116:119], s[14:15] offset:1024
	v_pk_mul_f32 v[88:89], v[6:7], v[88:89] op_sel_hi:[0,1]
	v_pk_mul_f32 v[90:91], v[6:7], v[90:91] op_sel_hi:[0,1]
	v_pk_mul_f32 v[120:121], v[152:153], v[88:89]
	v_pk_mul_f32 v[122:123], v[154:155], v[90:91]
	global_store_dwordx4 v2, v[120:123], s[14:15] offset:2048
	v_pk_mul_f32 v[92:93], v[6:7], v[92:93] op_sel_hi:[0,1]
	v_pk_mul_f32 v[94:95], v[6:7], v[94:95] op_sel_hi:[0,1]
	v_pk_mul_f32 v[124:125], v[156:157], v[92:93]
	v_pk_mul_f32 v[126:127], v[158:159], v[94:95]
	global_store_dwordx4 v2, v[124:127], s[14:15] offset:3072
	s_lshl_b32 s8, s2, 13
	s_add_u32 s14, s4, s8
	s_addc_u32 s15, s5, 0
	s_addk_i32 s2, 0x100
	s_lshl_b32 s8, s2, 12
	s_add_u32 s10, s6, s8
	s_addc_u32 s11, s7, 0
	global_load_dwordx2 v[20:21], v3, s[10:11] offset:-2048
	global_load_dwordx2 v[22:23], v3, s[10:11] offset:-1536
	global_load_dwordx2 v[24:25], v3, s[10:11] offset:-1024
	global_load_dwordx2 v[26:27], v3, s[10:11] offset:-512
	global_load_dwordx2 v[28:29], v3, s[10:11] offset:0
	global_load_dwordx2 v[30:31], v3, s[10:11] offset:512
	global_load_dwordx2 v[32:33], v3, s[10:11] offset:1024
	global_load_dwordx2 v[34:35], v3, s[10:11] offset:1536
	s_waitcnt vmcnt(16)
	v_lshlrev_b32_e32 v64, 16, v36
	v_and_b32_e32 v65, 0xffff0000, v36
	v_lshlrev_b32_e32 v66, 16, v37
	v_and_b32_e32 v67, 0xffff0000, v37
	v_mul_f32_e32 v8, v65, v65
	v_mul_f32_e32 v9, v67, v67
	v_fmac_f32_e32 v8, v64, v64
	v_fmac_f32_e32 v9, v66, v66
	v_add_f32_e32 v17, v8, v9
	v_lshlrev_b32_e32 v68, 16, v38
	v_and_b32_e32 v69, 0xffff0000, v38
	v_lshlrev_b32_e32 v70, 16, v39
	v_and_b32_e32 v71, 0xffff0000, v39
	v_mul_f32_e32 v8, v69, v69
	v_mul_f32_e32 v9, v71, v71
	v_fmac_f32_e32 v8, v68, v68
	v_fmac_f32_e32 v9, v70, v70
	v_add_f32_e32 v8, v8, v9
	v_add_f32_e32 v17, v17, v8
	v_lshlrev_b32_e32 v72, 16, v40
	v_and_b32_e32 v73, 0xffff0000, v40
	v_lshlrev_b32_e32 v74, 16, v41
	v_and_b32_e32 v75, 0xffff0000, v41
	v_mul_f32_e32 v8, v73, v73
	v_mul_f32_e32 v9, v75, v75
	v_fmac_f32_e32 v8, v72, v72
	v_fmac_f32_e32 v9, v74, v74
	v_add_f32_e32 v8, v8, v9
	v_add_f32_e32 v17, v17, v8
	v_lshlrev_b32_e32 v76, 16, v42
	v_and_b32_e32 v77, 0xffff0000, v42
	v_lshlrev_b32_e32 v78, 16, v43
	v_and_b32_e32 v79, 0xffff0000, v43
	v_mul_f32_e32 v8, v77, v77
	v_mul_f32_e32 v9, v79, v79
	v_fmac_f32_e32 v8, v76, v76
	v_fmac_f32_e32 v9, v78, v78
	v_add_f32_e32 v8, v8, v9
	v_add_f32_e32 v17, v17, v8
	v_lshlrev_b32_e32 v80, 16, v44
	v_and_b32_e32 v81, 0xffff0000, v44
	v_lshlrev_b32_e32 v82, 16, v45
	v_and_b32_e32 v83, 0xffff0000, v45
	v_mul_f32_e32 v8, v81, v81
	v_mul_f32_e32 v9, v83, v83
	v_fmac_f32_e32 v8, v80, v80
	v_fmac_f32_e32 v9, v82, v82
	v_add_f32_e32 v8, v8, v9
	v_add_f32_e32 v17, v17, v8
	v_lshlrev_b32_e32 v84, 16, v46
	v_and_b32_e32 v85, 0xffff0000, v46
	v_lshlrev_b32_e32 v86, 16, v47
	v_and_b32_e32 v87, 0xffff0000, v47
	v_mul_f32_e32 v8, v85, v85
	v_mul_f32_e32 v9, v87, v87
	v_fmac_f32_e32 v8, v84, v84
	v_fmac_f32_e32 v9, v86, v86
	v_add_f32_e32 v8, v8, v9
	v_add_f32_e32 v17, v17, v8
	v_lshlrev_b32_e32 v88, 16, v48
	v_and_b32_e32 v89, 0xffff0000, v48
	v_lshlrev_b32_e32 v90, 16, v49
	v_and_b32_e32 v91, 0xffff0000, v49
	v_mul_f32_e32 v8, v89, v89
	v_mul_f32_e32 v9, v91, v91
	v_fmac_f32_e32 v8, v88, v88
	v_fmac_f32_e32 v9, v90, v90
	v_add_f32_e32 v8, v8, v9
	v_add_f32_e32 v17, v17, v8
	v_lshlrev_b32_e32 v92, 16, v50
	v_and_b32_e32 v93, 0xffff0000, v50
	v_lshlrev_b32_e32 v94, 16, v51
	v_and_b32_e32 v95, 0xffff0000, v51
	v_mul_f32_e32 v8, v93, v93
	v_mul_f32_e32 v9, v95, v95
	v_fmac_f32_e32 v8, v92, v92
	v_fmac_f32_e32 v9, v94, v94
	v_add_f32_e32 v8, v8, v9
	v_add_f32_e32 v17, v17, v8
	ds_bpermute_b32 v18, v10, v17
	s_waitcnt lgkmcnt(0)
	v_add_f32_e32 v17, v17, v18
	ds_bpermute_b32 v18, v11, v17
	s_waitcnt lgkmcnt(0)
	v_add_f32_e32 v17, v17, v18
	ds_bpermute_b32 v18, v12, v17
	s_waitcnt lgkmcnt(0)
	v_add_f32_e32 v17, v17, v18
	ds_bpermute_b32 v18, v13, v17
	s_waitcnt lgkmcnt(0)
	v_add_f32_e32 v17, v17, v18
	ds_bpermute_b32 v18, v14, v17
	s_waitcnt lgkmcnt(0)
; __device__ __forceinline__ void final_norm_pass(const Ctx& C, const bf16* XB, const float* g, float* out) {
;     ...
;     for (int m = gw; m < M; m += NGW) {
;         const v2u* xr = (const v2u*)(XB + (size_t)m * D) + C.lane; f32x4 v[8]; float s = 0.f;
; #pragma unroll
;         for (int j = 0; j < 8; ++j) { const v2u w = xr[64 * j]; v[j] = (f32x4){__uint_as_float(w.x << 16), __uint_as_float(w.x & 0xffff0000u), __uint_as_float(w.y << 16), __uint_as_float(w.y & 0xffff0000u)};
;             s += (v[j][0] * v[j][0] + v[j][1] * v[j][1]) + (v[j][2] * v[j][2] + v[j][3] * v[j][3]); }
;         const float rstd = rsqrtf(wave_sum(s) * (1.0f / D) + EPS);
;         const f32x4* gr = (const f32x4*)g + C.lane; f32x4* o = (f32x4*)(out + (size_t)m * D) + C.lane;
; #pragma unroll
;         for (int j = 0; j < 8; ++j) o[64 * j] = v[j] * rstd * gr[64 * j];
;     }
	v_add_f32_e32 v17, v17, v18
	ds_bpermute_b32 v18, v15, v17
	s_waitcnt lgkmcnt(0)
	v_add_f32_e32 v17, v17, v18
	v_fmamk_f32 v6, v17, 0x3a000000, v5
	v_rsq_f32_e32 v6, v6
	s_nop 0
	v_pk_mul_f32 v[64:65], v[6:7], v[64:65] op_sel_hi:[0,1]
	v_pk_mul_f32 v[66:67], v[6:7], v[66:67] op_sel_hi:[0,1]
	v_pk_mul_f32 v[96:97], v[128:129], v[64:65]
	v_pk_mul_f32 v[98:99], v[130:131], v[66:67]
	global_store_dwordx4 v2, v[96:99], s[14:15] offset:-4096
	v_pk_mul_f32 v[68:69], v[6:7], v[68:69] op_sel_hi:[0,1]
	v_pk_mul_f32 v[70:71], v[6:7], v[70:71] op_sel_hi:[0,1]
	v_pk_mul_f32 v[100:101], v[132:133], v[68:69]
	v_pk_mul_f32 v[102:103], v[134:135], v[70:71]
	global_store_dwordx4 v2, v[100:103], s[14:15] offset:-3072
	v_pk_mul_f32 v[72:73], v[6:7], v[72:73] op_sel_hi:[0,1]
	v_pk_mul_f32 v[74:75], v[6:7], v[74:75] op_sel_hi:[0,1]
	v_pk_mul_f32 v[104:105], v[136:137], v[72:73]
	v_pk_mul_f32 v[106:107], v[138:139], v[74:75]
	global_store_dwordx4 v2, v[104:107], s[14:15] offset:-2048
	v_pk_mul_f32 v[76:77], v[6:7], v[76:77] op_sel_hi:[0,1]
	v_pk_mul_f32 v[78:79], v[6:7], v[78:79] op_sel_hi:[0,1]
	v_pk_mul_f32 v[108:109], v[140:141], v[76:77]
	v_pk_mul_f32 v[110:111], v[142:143], v[78:79]
	global_store_dwordx4 v2, v[108:111], s[14:15] offset:-1024
	v_pk_mul_f32 v[80:81], v[6:7], v[80:81] op_sel_hi:[0,1]
	v_pk_mul_f32 v[82:83], v[6:7], v[82:83] op_sel_hi:[0,1]
	v_pk_mul_f32 v[112:113], v[144:145], v[80:81]
	v_pk_mul_f32 v[114:115], v[146:147], v[82:83]
	global_store_dwordx4 v2, v[112:115], s[14:15] offset:0
	v_pk_mul_f32 v[84:85], v[6:7], v[84:85] op_sel_hi:[0,1]
	v_pk_mul_f32 v[86:87], v[6:7], v[86:87] op_sel_hi:[0,1]
	v_pk_mul_f32 v[116:117], v[148:149], v[84:85]
	v_pk_mul_f32 v[118:119], v[150:151], v[86:87]
	global_store_dwordx4 v2, v[116:119], s[14:15] offset:1024
	v_pk_mul_f32 v[88:89], v[6:7], v[88:89] op_sel_hi:[0,1]
	v_pk_mul_f32 v[90:91], v[6:7], v[90:91] op_sel_hi:[0,1]
	v_pk_mul_f32 v[120:121], v[152:153], v[88:89]
	v_pk_mul_f32 v[122:123], v[154:155], v[90:91]
	global_store_dwordx4 v2, v[120:123], s[14:15] offset:2048
	v_pk_mul_f32 v[92:93], v[6:7], v[92:93] op_sel_hi:[0,1]
	v_pk_mul_f32 v[94:95], v[6:7], v[94:95] op_sel_hi:[0,1]
	v_pk_mul_f32 v[124:125], v[156:157], v[92:93]
	v_pk_mul_f32 v[126:127], v[158:159], v[94:95]
	global_store_dwordx4 v2, v[124:127], s[14:15] offset:3072
	s_lshl_b32 s8, s2, 13
	s_add_u32 s14, s4, s8
	s_addc_u32 s15, s5, 0
	s_addk_i32 s2, 0x100
	s_lshl_b32 s8, s2, 12
	s_add_u32 s10, s6, s8
	s_addc_u32 s11, s7, 0
	global_load_dwordx2 v[36:37], v3, s[10:11] offset:-2048
	global_load_dwordx2 v[38:39], v3, s[10:11] offset:-1536
	global_load_dwordx2 v[40:41], v3, s[10:11] offset:-1024
	global_load_dwordx2 v[42:43], v3, s[10:11] offset:-512
	global_load_dwordx2 v[44:45], v3, s[10:11] offset:0
	global_load_dwordx2 v[46:47], v3, s[10:11] offset:512
	global_load_dwordx2 v[48:49], v3, s[10:11] offset:1024
	global_load_dwordx2 v[50:51], v3, s[10:11] offset:1536
	s_waitcnt vmcnt(16)
	v_lshlrev_b32_e32 v64, 16, v20
	v_and_b32_e32 v65, 0xffff0000, v20
	v_lshlrev_b32_e32 v66, 16, v21
	v_and_b32_e32 v67, 0xffff0000, v21
	v_mul_f32_e32 v8, v65, v65
	v_mul_f32_e32 v9, v67, v67
	v_fmac_f32_e32 v8, v64, v64
	v_fmac_f32_e32 v9, v66, v66
	v_add_f32_e32 v17, v8, v9
	v_lshlrev_b32_e32 v68, 16, v22
	v_and_b32_e32 v69, 0xffff0000, v22
	v_lshlrev_b32_e32 v70, 16, v23
	v_and_b32_e32 v71, 0xffff0000, v23
	v_mul_f32_e32 v8, v69, v69
	v_mul_f32_e32 v9, v71, v71
	v_fmac_f32_e32 v8, v68, v68
	v_fmac_f32_e32 v9, v70, v70
	v_add_f32_e32 v8, v8, v9
	v_add_f32_e32 v17, v17, v8
	v_lshlrev_b32_e32 v72, 16, v24
	v_and_b32_e32 v73, 0xffff0000, v24
	v_lshlrev_b32_e32 v74, 16, v25
	v_and_b32_e32 v75, 0xffff0000, v25
	v_mul_f32_e32 v8, v73, v73
	v_mul_f32_e32 v9, v75, v75
	v_fmac_f32_e32 v8, v72, v72
	v_fmac_f32_e32 v9, v74, v74
	v_add_f32_e32 v8, v8, v9
	v_add_f32_e32 v17, v17, v8
	v_lshlrev_b32_e32 v76, 16, v26
	v_and_b32_e32 v77, 0xffff0000, v26
	v_lshlrev_b32_e32 v78, 16, v27
	v_and_b32_e32 v79, 0xffff0000, v27
	v_mul_f32_e32 v8, v77, v77
	v_mul_f32_e32 v9, v79, v79
	v_fmac_f32_e32 v8, v76, v76
	v_fmac_f32_e32 v9, v78, v78
	v_add_f32_e32 v8, v8, v9
	v_add_f32_e32 v17, v17, v8
	v_lshlrev_b32_e32 v80, 16, v28
	v_and_b32_e32 v81, 0xffff0000, v28
	v_lshlrev_b32_e32 v82, 16, v29
	v_and_b32_e32 v83, 0xffff0000, v29
	v_mul_f32_e32 v8, v81, v81
	v_mul_f32_e32 v9, v83, v83
	v_fmac_f32_e32 v8, v80, v80
	v_fmac_f32_e32 v9, v82, v82
	v_add_f32_e32 v8, v8, v9
	v_add_f32_e32 v17, v17, v8
	v_lshlrev_b32_e32 v84, 16, v30
	v_and_b32_e32 v85, 0xffff0000, v30
	v_lshlrev_b32_e32 v86, 16, v31
	v_and_b32_e32 v87, 0xffff0000, v31
	v_mul_f32_e32 v8, v85, v85
	v_mul_f32_e32 v9, v87, v87
	v_fmac_f32_e32 v8, v84, v84
	v_fmac_f32_e32 v9, v86, v86
	v_add_f32_e32 v8, v8, v9
	v_add_f32_e32 v17, v17, v8
	v_lshlrev_b32_e32 v88, 16, v32
	v_and_b32_e32 v89, 0xffff0000, v32
	v_lshlrev_b32_e32 v90, 16, v33
	v_and_b32_e32 v91, 0xffff0000, v33
	v_mul_f32_e32 v8, v89, v89
	v_mul_f32_e32 v9, v91, v91
	v_fmac_f32_e32 v8, v88, v88
	v_fmac_f32_e32 v9, v90, v90
	v_add_f32_e32 v8, v8, v9
	v_add_f32_e32 v17, v17, v8
	v_lshlrev_b32_e32 v92, 16, v34
	v_and_b32_e32 v93, 0xffff0000, v34
	v_lshlrev_b32_e32 v94, 16, v35
	v_and_b32_e32 v95, 0xffff0000, v35
	v_mul_f32_e32 v8, v93, v93
	v_mul_f32_e32 v9, v95, v95
	v_fmac_f32_e32 v8, v92, v92
	v_fmac_f32_e32 v9, v94, v94
	v_add_f32_e32 v8, v8, v9
	v_add_f32_e32 v17, v17, v8
	ds_bpermute_b32 v18, v10, v17
	s_waitcnt lgkmcnt(0)
	v_add_f32_e32 v17, v17, v18
	ds_bpermute_b32 v18, v11, v17
	s_waitcnt lgkmcnt(0)
	v_add_f32_e32 v17, v17, v18
	ds_bpermute_b32 v18, v12, v17
	s_waitcnt lgkmcnt(0)
	v_add_f32_e32 v17, v17, v18
	ds_bpermute_b32 v18, v13, v17
	s_waitcnt lgkmcnt(0)
; __device__ __forceinline__ void final_norm_pass(const Ctx& C, const bf16* XB, const float* g, float* out) {
;     ...
;     for (int m = gw; m < M; m += NGW) {
;         const v2u* xr = (const v2u*)(XB + (size_t)m * D) + C.lane; f32x4 v[8]; float s = 0.f;
; #pragma unroll
;         for (int j = 0; j < 8; ++j) { const v2u w = xr[64 * j]; v[j] = (f32x4){__uint_as_float(w.x << 16), __uint_as_float(w.x & 0xffff0000u), __uint_as_float(w.y << 16), __uint_as_float(w.y & 0xffff0000u)};
;             s += (v[j][0] * v[j][0] + v[j][1] * v[j][1]) + (v[j][2] * v[j][2] + v[j][3] * v[j][3]); }
;         const float rstd = rsqrtf(wave_sum(s) * (1.0f / D) + EPS);
;         const f32x4* gr = (const f32x4*)g + C.lane; f32x4* o = (f32x4*)(out + (size_t)m * D) + C.lane;
; #pragma unroll
;         for (int j = 0; j < 8; ++j) o[64 * j] = v[j] * rstd * gr[64 * j];
;     }
	v_add_f32_e32 v17, v17, v18
	ds_bpermute_b32 v18, v14, v17
	s_waitcnt lgkmcnt(0)
	v_add_f32_e32 v17, v17, v18
	ds_bpermute_b32 v18, v15, v17
	s_waitcnt lgkmcnt(0)
	v_add_f32_e32 v17, v17, v18
	v_fmamk_f32 v6, v17, 0x3a000000, v5
	v_rsq_f32_e32 v6, v6
	s_nop 0
	v_pk_mul_f32 v[64:65], v[6:7], v[64:65] op_sel_hi:[0,1]
	v_pk_mul_f32 v[66:67], v[6:7], v[66:67] op_sel_hi:[0,1]
	v_pk_mul_f32 v[96:97], v[128:129], v[64:65]
	v_pk_mul_f32 v[98:99], v[130:131], v[66:67]
	global_store_dwordx4 v2, v[96:99], s[14:15] offset:-4096
	v_pk_mul_f32 v[68:69], v[6:7], v[68:69] op_sel_hi:[0,1]
	v_pk_mul_f32 v[70:71], v[6:7], v[70:71] op_sel_hi:[0,1]
	v_pk_mul_f32 v[100:101], v[132:133], v[68:69]
	v_pk_mul_f32 v[102:103], v[134:135], v[70:71]
	global_store_dwordx4 v2, v[100:103], s[14:15] offset:-3072
	v_pk_mul_f32 v[72:73], v[6:7], v[72:73] op_sel_hi:[0,1]
	v_pk_mul_f32 v[74:75], v[6:7], v[74:75] op_sel_hi:[0,1]
	v_pk_mul_f32 v[104:105], v[136:137], v[72:73]
	v_pk_mul_f32 v[106:107], v[138:139], v[74:75]
	global_store_dwordx4 v2, v[104:107], s[14:15] offset:-2048
	v_pk_mul_f32 v[76:77], v[6:7], v[76:77] op_sel_hi:[0,1]
	v_pk_mul_f32 v[78:79], v[6:7], v[78:79] op_sel_hi:[0,1]
	v_pk_mul_f32 v[108:109], v[140:141], v[76:77]
	v_pk_mul_f32 v[110:111], v[142:143], v[78:79]
	global_store_dwordx4 v2, v[108:111], s[14:15] offset:-1024
	v_pk_mul_f32 v[80:81], v[6:7], v[80:81] op_sel_hi:[0,1]
	v_pk_mul_f32 v[82:83], v[6:7], v[82:83] op_sel_hi:[0,1]
	v_pk_mul_f32 v[112:113], v[144:145], v[80:81]
	v_pk_mul_f32 v[114:115], v[146:147], v[82:83]
	global_store_dwordx4 v2, v[112:115], s[14:15] offset:0
	v_pk_mul_f32 v[84:85], v[6:7], v[84:85] op_sel_hi:[0,1]
	v_pk_mul_f32 v[86:87], v[6:7], v[86:87] op_sel_hi:[0,1]
	v_pk_mul_f32 v[116:117], v[148:149], v[84:85]
	v_pk_mul_f32 v[118:119], v[150:151], v[86:87]
	global_store_dwordx4 v2, v[116:119], s[14:15] offset:1024
	v_pk_mul_f32 v[88:89], v[6:7], v[88:89] op_sel_hi:[0,1]
	v_pk_mul_f32 v[90:91], v[6:7], v[90:91] op_sel_hi:[0,1]
	v_pk_mul_f32 v[120:121], v[152:153], v[88:89]
	v_pk_mul_f32 v[122:123], v[154:155], v[90:91]
	global_store_dwordx4 v2, v[120:123], s[14:15] offset:2048
	v_pk_mul_f32 v[92:93], v[6:7], v[92:93] op_sel_hi:[0,1]
	v_pk_mul_f32 v[94:95], v[6:7], v[94:95] op_sel_hi:[0,1]
	v_pk_mul_f32 v[124:125], v[156:157], v[92:93]
	v_pk_mul_f32 v[126:127], v[158:159], v[94:95]
	global_store_dwordx4 v2, v[124:127], s[14:15] offset:3072
	s_lshl_b32 s8, s2, 13
	s_add_u32 s14, s4, s8
	s_addc_u32 s15, s5, 0
	s_addk_i32 s2, 0x100
	s_lshl_b32 s8, s2, 12
	s_add_u32 s10, s6, s8
	s_addc_u32 s11, s7, 0
	global_load_dwordx2 v[20:21], v3, s[10:11] offset:-2048
	global_load_dwordx2 v[22:23], v3, s[10:11] offset:-1536
	global_load_dwordx2 v[24:25], v3, s[10:11] offset:-1024
	global_load_dwordx2 v[26:27], v3, s[10:11] offset:-512
	global_load_dwordx2 v[28:29], v3, s[10:11] offset:0
	global_load_dwordx2 v[30:31], v3, s[10:11] offset:512
	global_load_dwordx2 v[32:33], v3, s[10:11] offset:1024
	global_load_dwordx2 v[34:35], v3, s[10:11] offset:1536
	s_waitcnt vmcnt(16)
	v_lshlrev_b32_e32 v64, 16, v36
	v_and_b32_e32 v65, 0xffff0000, v36
	v_lshlrev_b32_e32 v66, 16, v37
	v_and_b32_e32 v67, 0xffff0000, v37
	v_mul_f32_e32 v8, v65, v65
	v_mul_f32_e32 v9, v67, v67
	v_fmac_f32_e32 v8, v64, v64
	v_fmac_f32_e32 v9, v66, v66
	v_add_f32_e32 v17, v8, v9
	v_lshlrev_b32_e32 v68, 16, v38
	v_and_b32_e32 v69, 0xffff0000, v38
	v_lshlrev_b32_e32 v70, 16, v39
	v_and_b32_e32 v71, 0xffff0000, v39
	v_mul_f32_e32 v8, v69, v69
	v_mul_f32_e32 v9, v71, v71
	v_fmac_f32_e32 v8, v68, v68
	v_fmac_f32_e32 v9, v70, v70
	v_add_f32_e32 v8, v8, v9
	v_add_f32_e32 v17, v17, v8
	v_lshlrev_b32_e32 v72, 16, v40
	v_and_b32_e32 v73, 0xffff0000, v40
	v_lshlrev_b32_e32 v74, 16, v41
	v_and_b32_e32 v75, 0xffff0000, v41
	v_mul_f32_e32 v8, v73, v73
	v_mul_f32_e32 v9, v75, v75
	v_fmac_f32_e32 v8, v72, v72
	v_fmac_f32_e32 v9, v74, v74
	v_add_f32_e32 v8, v8, v9
	v_add_f32_e32 v17, v17, v8
	v_lshlrev_b32_e32 v76, 16, v42
	v_and_b32_e32 v77, 0xffff0000, v42
	v_lshlrev_b32_e32 v78, 16, v43
	v_and_b32_e32 v79, 0xffff0000, v43
	v_mul_f32_e32 v8, v77, v77
	v_mul_f32_e32 v9, v79, v79
	v_fmac_f32_e32 v8, v76, v76
	v_fmac_f32_e32 v9, v78, v78
	v_add_f32_e32 v8, v8, v9
	v_add_f32_e32 v17, v17, v8
	v_lshlrev_b32_e32 v80, 16, v44
	v_and_b32_e32 v81, 0xffff0000, v44
	v_lshlrev_b32_e32 v82, 16, v45
	v_and_b32_e32 v83, 0xffff0000, v45
	v_mul_f32_e32 v8, v81, v81
	v_mul_f32_e32 v9, v83, v83
	v_fmac_f32_e32 v8, v80, v80
	v_fmac_f32_e32 v9, v82, v82
	v_add_f32_e32 v8, v8, v9
	v_add_f32_e32 v17, v17, v8
	v_lshlrev_b32_e32 v84, 16, v46
	v_and_b32_e32 v85, 0xffff0000, v46
	v_lshlrev_b32_e32 v86, 16, v47
	v_and_b32_e32 v87, 0xffff0000, v47
	v_mul_f32_e32 v8, v85, v85
	v_mul_f32_e32 v9, v87, v87
	v_fmac_f32_e32 v8, v84, v84
	v_fmac_f32_e32 v9, v86, v86
	v_add_f32_e32 v8, v8, v9
	v_add_f32_e32 v17, v17, v8
	v_lshlrev_b32_e32 v88, 16, v48
	v_and_b32_e32 v89, 0xffff0000, v48
	v_lshlrev_b32_e32 v90, 16, v49
	v_and_b32_e32 v91, 0xffff0000, v49
	v_mul_f32_e32 v8, v89, v89
	v_mul_f32_e32 v9, v91, v91
	v_fmac_f32_e32 v8, v88, v88
	v_fmac_f32_e32 v9, v90, v90
	v_add_f32_e32 v8, v8, v9
	v_add_f32_e32 v17, v17, v8
	v_lshlrev_b32_e32 v92, 16, v50
	v_and_b32_e32 v93, 0xffff0000, v50
	v_lshlrev_b32_e32 v94, 16, v51
	v_and_b32_e32 v95, 0xffff0000, v51
	v_mul_f32_e32 v8, v93, v93
	v_mul_f32_e32 v9, v95, v95
	v_fmac_f32_e32 v8, v92, v92
	v_fmac_f32_e32 v9, v94, v94
	v_add_f32_e32 v8, v8, v9
	v_add_f32_e32 v17, v17, v8
	ds_bpermute_b32 v18, v10, v17
	s_waitcnt lgkmcnt(0)
	v_add_f32_e32 v17, v17, v18
	ds_bpermute_b32 v18, v11, v17
	s_waitcnt lgkmcnt(0)
	v_add_f32_e32 v17, v17, v18
	ds_bpermute_b32 v18, v12, v17
	s_waitcnt lgkmcnt(0)
; __device__ __forceinline__ void final_norm_pass(const Ctx& C, const bf16* XB, const float* g, float* out) {
;     ...
;     for (int m = gw; m < M; m += NGW) {
;         const v2u* xr = (const v2u*)(XB + (size_t)m * D) + C.lane; f32x4 v[8]; float s = 0.f;
; #pragma unroll
;         for (int j = 0; j < 8; ++j) { const v2u w = xr[64 * j]; v[j] = (f32x4){__uint_as_float(w.x << 16), __uint_as_float(w.x & 0xffff0000u), __uint_as_float(w.y << 16), __uint_as_float(w.y & 0xffff0000u)};
;             s += (v[j][0] * v[j][0] + v[j][1] * v[j][1]) + (v[j][2] * v[j][2] + v[j][3] * v[j][3]); }
;         const float rstd = rsqrtf(wave_sum(s) * (1.0f / D) + EPS);
;         const f32x4* gr = (const f32x4*)g + C.lane; f32x4* o = (f32x4*)(out + (size_t)m * D) + C.lane;
; #pragma unroll
;         for (int j = 0; j < 8; ++j) o[64 * j] = v[j] * rstd * gr[64 * j];
;     }
	v_add_f32_e32 v17, v17, v18
	ds_bpermute_b32 v18, v13, v17
	s_waitcnt lgkmcnt(0)
	v_add_f32_e32 v17, v17, v18
	ds_bpermute_b32 v18, v14, v17
	s_waitcnt lgkmcnt(0)
	v_add_f32_e32 v17, v17, v18
	ds_bpermute_b32 v18, v15, v17
	s_waitcnt lgkmcnt(0)
	v_add_f32_e32 v17, v17, v18
	v_fmamk_f32 v6, v17, 0x3a000000, v5
	v_rsq_f32_e32 v6, v6
	s_nop 0
	v_pk_mul_f32 v[64:65], v[6:7], v[64:65] op_sel_hi:[0,1]
	v_pk_mul_f32 v[66:67], v[6:7], v[66:67] op_sel_hi:[0,1]
	v_pk_mul_f32 v[96:97], v[128:129], v[64:65]
	v_pk_mul_f32 v[98:99], v[130:131], v[66:67]
	global_store_dwordx4 v2, v[96:99], s[14:15] offset:-4096
	v_pk_mul_f32 v[68:69], v[6:7], v[68:69] op_sel_hi:[0,1]
	v_pk_mul_f32 v[70:71], v[6:7], v[70:71] op_sel_hi:[0,1]
	v_pk_mul_f32 v[100:101], v[132:133], v[68:69]
	v_pk_mul_f32 v[102:103], v[134:135], v[70:71]
	global_store_dwordx4 v2, v[100:103], s[14:15] offset:-3072
	v_pk_mul_f32 v[72:73], v[6:7], v[72:73] op_sel_hi:[0,1]
	v_pk_mul_f32 v[74:75], v[6:7], v[74:75] op_sel_hi:[0,1]
	v_pk_mul_f32 v[104:105], v[136:137], v[72:73]
	v_pk_mul_f32 v[106:107], v[138:139], v[74:75]
	global_store_dwordx4 v2, v[104:107], s[14:15] offset:-2048
	v_pk_mul_f32 v[76:77], v[6:7], v[76:77] op_sel_hi:[0,1]
	v_pk_mul_f32 v[78:79], v[6:7], v[78:79] op_sel_hi:[0,1]
	v_pk_mul_f32 v[108:109], v[140:141], v[76:77]
	v_pk_mul_f32 v[110:111], v[142:143], v[78:79]
	global_store_dwordx4 v2, v[108:111], s[14:15] offset:-1024
	v_pk_mul_f32 v[80:81], v[6:7], v[80:81] op_sel_hi:[0,1]
	v_pk_mul_f32 v[82:83], v[6:7], v[82:83] op_sel_hi:[0,1]
	v_pk_mul_f32 v[112:113], v[144:145], v[80:81]
	v_pk_mul_f32 v[114:115], v[146:147], v[82:83]
	global_store_dwordx4 v2, v[112:115], s[14:15] offset:0
	v_pk_mul_f32 v[84:85], v[6:7], v[84:85] op_sel_hi:[0,1]
	v_pk_mul_f32 v[86:87], v[6:7], v[86:87] op_sel_hi:[0,1]
	v_pk_mul_f32 v[116:117], v[148:149], v[84:85]
	v_pk_mul_f32 v[118:119], v[150:151], v[86:87]
	global_store_dwordx4 v2, v[116:119], s[14:15] offset:1024
	v_pk_mul_f32 v[88:89], v[6:7], v[88:89] op_sel_hi:[0,1]
	v_pk_mul_f32 v[90:91], v[6:7], v[90:91] op_sel_hi:[0,1]
	v_pk_mul_f32 v[120:121], v[152:153], v[88:89]
	v_pk_mul_f32 v[122:123], v[154:155], v[90:91]
	global_store_dwordx4 v2, v[120:123], s[14:15] offset:2048
	v_pk_mul_f32 v[92:93], v[6:7], v[92:93] op_sel_hi:[0,1]
	v_pk_mul_f32 v[94:95], v[6:7], v[94:95] op_sel_hi:[0,1]
	v_pk_mul_f32 v[124:125], v[156:157], v[92:93]
	v_pk_mul_f32 v[126:127], v[158:159], v[94:95]
	global_store_dwordx4 v2, v[124:127], s[14:15] offset:3072
	s_lshl_b32 s8, s2, 13
	s_add_u32 s14, s4, s8
	s_addc_u32 s15, s5, 0
	s_addk_i32 s2, 0x100
	s_lshl_b32 s8, s2, 12
	s_add_u32 s10, s6, s8
	s_addc_u32 s11, s7, 0
	global_load_dwordx2 v[36:37], v3, s[10:11] offset:-2048
	global_load_dwordx2 v[38:39], v3, s[10:11] offset:-1536
	global_load_dwordx2 v[40:41], v3, s[10:11] offset:-1024
	global_load_dwordx2 v[42:43], v3, s[10:11] offset:-512
	global_load_dwordx2 v[44:45], v3, s[10:11] offset:0
	global_load_dwordx2 v[46:47], v3, s[10:11] offset:512
	global_load_dwordx2 v[48:49], v3, s[10:11] offset:1024
	global_load_dwordx2 v[50:51], v3, s[10:11] offset:1536
	s_waitcnt vmcnt(16)
	v_lshlrev_b32_e32 v64, 16, v20
	v_and_b32_e32 v65, 0xffff0000, v20
	v_lshlrev_b32_e32 v66, 16, v21
	v_and_b32_e32 v67, 0xffff0000, v21
	v_mul_f32_e32 v8, v65, v65
	v_mul_f32_e32 v9, v67, v67
	v_fmac_f32_e32 v8, v64, v64
	v_fmac_f32_e32 v9, v66, v66
	v_add_f32_e32 v17, v8, v9
	v_lshlrev_b32_e32 v68, 16, v22
	v_and_b32_e32 v69, 0xffff0000, v22
	v_lshlrev_b32_e32 v70, 16, v23
	v_and_b32_e32 v71, 0xffff0000, v23
	v_mul_f32_e32 v8, v69, v69
	v_mul_f32_e32 v9, v71, v71
	v_fmac_f32_e32 v8, v68, v68
	v_fmac_f32_e32 v9, v70, v70
	v_add_f32_e32 v8, v8, v9
	v_add_f32_e32 v17, v17, v8
	v_lshlrev_b32_e32 v72, 16, v24
	v_and_b32_e32 v73, 0xffff0000, v24
	v_lshlrev_b32_e32 v74, 16, v25
	v_and_b32_e32 v75, 0xffff0000, v25
	v_mul_f32_e32 v8, v73, v73
	v_mul_f32_e32 v9, v75, v75
	v_fmac_f32_e32 v8, v72, v72
	v_fmac_f32_e32 v9, v74, v74
	v_add_f32_e32 v8, v8, v9
	v_add_f32_e32 v17, v17, v8
	v_lshlrev_b32_e32 v76, 16, v26
	v_and_b32_e32 v77, 0xffff0000, v26
	v_lshlrev_b32_e32 v78, 16, v27
	v_and_b32_e32 v79, 0xffff0000, v27
	v_mul_f32_e32 v8, v77, v77
	v_mul_f32_e32 v9, v79, v79
	v_fmac_f32_e32 v8, v76, v76
	v_fmac_f32_e32 v9, v78, v78
	v_add_f32_e32 v8, v8, v9
	v_add_f32_e32 v17, v17, v8
	v_lshlrev_b32_e32 v80, 16, v28
	v_and_b32_e32 v81, 0xffff0000, v28
	v_lshlrev_b32_e32 v82, 16, v29
	v_and_b32_e32 v83, 0xffff0000, v29
	v_mul_f32_e32 v8, v81, v81
	v_mul_f32_e32 v9, v83, v83
	v_fmac_f32_e32 v8, v80, v80
	v_fmac_f32_e32 v9, v82, v82
	v_add_f32_e32 v8, v8, v9
	v_add_f32_e32 v17, v17, v8
	v_lshlrev_b32_e32 v84, 16, v30
	v_and_b32_e32 v85, 0xffff0000, v30
	v_lshlrev_b32_e32 v86, 16, v31
	v_and_b32_e32 v87, 0xffff0000, v31
	v_mul_f32_e32 v8, v85, v85
	v_mul_f32_e32 v9, v87, v87
	v_fmac_f32_e32 v8, v84, v84
	v_fmac_f32_e32 v9, v86, v86
	v_add_f32_e32 v8, v8, v9
	v_add_f32_e32 v17, v17, v8
	v_lshlrev_b32_e32 v88, 16, v32
	v_and_b32_e32 v89, 0xffff0000, v32
	v_lshlrev_b32_e32 v90, 16, v33
	v_and_b32_e32 v91, 0xffff0000, v33
	v_mul_f32_e32 v8, v89, v89
	v_mul_f32_e32 v9, v91, v91
	v_fmac_f32_e32 v8, v88, v88
	v_fmac_f32_e32 v9, v90, v90
	v_add_f32_e32 v8, v8, v9
	v_add_f32_e32 v17, v17, v8
	v_lshlrev_b32_e32 v92, 16, v34
	v_and_b32_e32 v93, 0xffff0000, v34
	v_lshlrev_b32_e32 v94, 16, v35
	v_and_b32_e32 v95, 0xffff0000, v35
	v_mul_f32_e32 v8, v93, v93
	v_mul_f32_e32 v9, v95, v95
	v_fmac_f32_e32 v8, v92, v92
	v_fmac_f32_e32 v9, v94, v94
	v_add_f32_e32 v8, v8, v9
	v_add_f32_e32 v17, v17, v8
	ds_bpermute_b32 v18, v10, v17
	s_waitcnt lgkmcnt(0)
	v_add_f32_e32 v17, v17, v18
	ds_bpermute_b32 v18, v11, v17
	s_waitcnt lgkmcnt(0)
; __device__ __forceinline__ void final_norm_pass(const Ctx& C, const bf16* XB, const float* g, float* out) {
;     ...
;     for (int m = gw; m < M; m += NGW) {
;         const v2u* xr = (const v2u*)(XB + (size_t)m * D) + C.lane; f32x4 v[8]; float s = 0.f;
; #pragma unroll
;         for (int j = 0; j < 8; ++j) { const v2u w = xr[64 * j]; v[j] = (f32x4){__uint_as_float(w.x << 16), __uint_as_float(w.x & 0xffff0000u), __uint_as_float(w.y << 16), __uint_as_float(w.y & 0xffff0000u)};
;             s += (v[j][0] * v[j][0] + v[j][1] * v[j][1]) + (v[j][2] * v[j][2] + v[j][3] * v[j][3]); }
;         const float rstd = rsqrtf(wave_sum(s) * (1.0f / D) + EPS);
;         const f32x4* gr = (const f32x4*)g + C.lane; f32x4* o = (f32x4*)(out + (size_t)m * D) + C.lane;
; #pragma unroll
;         for (int j = 0; j < 8; ++j) o[64 * j] = v[j] * rstd * gr[64 * j];
;     }
	v_add_f32_e32 v17, v17, v18
	ds_bpermute_b32 v18, v12, v17
	s_waitcnt lgkmcnt(0)
	v_add_f32_e32 v17, v17, v18
	ds_bpermute_b32 v18, v13, v17
	s_waitcnt lgkmcnt(0)
	v_add_f32_e32 v17, v17, v18
	ds_bpermute_b32 v18, v14, v17
	s_waitcnt lgkmcnt(0)
	v_add_f32_e32 v17, v17, v18
	ds_bpermute_b32 v18, v15, v17
	s_waitcnt lgkmcnt(0)
	v_add_f32_e32 v17, v17, v18
	v_fmamk_f32 v6, v17, 0x3a000000, v5
	v_rsq_f32_e32 v6, v6
	s_nop 0
	v_pk_mul_f32 v[64:65], v[6:7], v[64:65] op_sel_hi:[0,1]
	v_pk_mul_f32 v[66:67], v[6:7], v[66:67] op_sel_hi:[0,1]
	v_pk_mul_f32 v[96:97], v[128:129], v[64:65]
	v_pk_mul_f32 v[98:99], v[130:131], v[66:67]
	global_store_dwordx4 v2, v[96:99], s[14:15] offset:-4096
	v_pk_mul_f32 v[68:69], v[6:7], v[68:69] op_sel_hi:[0,1]
	v_pk_mul_f32 v[70:71], v[6:7], v[70:71] op_sel_hi:[0,1]
	v_pk_mul_f32 v[100:101], v[132:133], v[68:69]
	v_pk_mul_f32 v[102:103], v[134:135], v[70:71]
	global_store_dwordx4 v2, v[100:103], s[14:15] offset:-3072
	v_pk_mul_f32 v[72:73], v[6:7], v[72:73] op_sel_hi:[0,1]
	v_pk_mul_f32 v[74:75], v[6:7], v[74:75] op_sel_hi:[0,1]
	v_pk_mul_f32 v[104:105], v[136:137], v[72:73]
	v_pk_mul_f32 v[106:107], v[138:139], v[74:75]
	global_store_dwordx4 v2, v[104:107], s[14:15] offset:-2048
	v_pk_mul_f32 v[76:77], v[6:7], v[76:77] op_sel_hi:[0,1]
	v_pk_mul_f32 v[78:79], v[6:7], v[78:79] op_sel_hi:[0,1]
	v_pk_mul_f32 v[108:109], v[140:141], v[76:77]
	v_pk_mul_f32 v[110:111], v[142:143], v[78:79]
	global_store_dwordx4 v2, v[108:111], s[14:15] offset:-1024
	v_pk_mul_f32 v[80:81], v[6:7], v[80:81] op_sel_hi:[0,1]
	v_pk_mul_f32 v[82:83], v[6:7], v[82:83] op_sel_hi:[0,1]
	v_pk_mul_f32 v[112:113], v[144:145], v[80:81]
	v_pk_mul_f32 v[114:115], v[146:147], v[82:83]
	global_store_dwordx4 v2, v[112:115], s[14:15] offset:0
	v_pk_mul_f32 v[84:85], v[6:7], v[84:85] op_sel_hi:[0,1]
	v_pk_mul_f32 v[86:87], v[6:7], v[86:87] op_sel_hi:[0,1]
	v_pk_mul_f32 v[116:117], v[148:149], v[84:85]
	v_pk_mul_f32 v[118:119], v[150:151], v[86:87]
	global_store_dwordx4 v2, v[116:119], s[14:15] offset:1024
	v_pk_mul_f32 v[88:89], v[6:7], v[88:89] op_sel_hi:[0,1]
	v_pk_mul_f32 v[90:91], v[6:7], v[90:91] op_sel_hi:[0,1]
	v_pk_mul_f32 v[120:121], v[152:153], v[88:89]
	v_pk_mul_f32 v[122:123], v[154:155], v[90:91]
	global_store_dwordx4 v2, v[120:123], s[14:15] offset:2048
	v_pk_mul_f32 v[92:93], v[6:7], v[92:93] op_sel_hi:[0,1]
	v_pk_mul_f32 v[94:95], v[6:7], v[94:95] op_sel_hi:[0,1]
	v_pk_mul_f32 v[124:125], v[156:157], v[92:93]
	v_pk_mul_f32 v[126:127], v[158:159], v[94:95]
	global_store_dwordx4 v2, v[124:127], s[14:15] offset:3072
	s_lshl_b32 s8, s2, 13
	s_add_u32 s14, s4, s8
	s_addc_u32 s15, s5, 0
	s_addk_i32 s2, 0x100
	s_lshl_b32 s8, s2, 12
	s_add_u32 s10, s6, s8
	s_addc_u32 s11, s7, 0
	global_load_dwordx2 v[20:21], v3, s[10:11] offset:-2048
	global_load_dwordx2 v[22:23], v3, s[10:11] offset:-1536
	global_load_dwordx2 v[24:25], v3, s[10:11] offset:-1024
	global_load_dwordx2 v[26:27], v3, s[10:11] offset:-512
	global_load_dwordx2 v[28:29], v3, s[10:11] offset:0
	global_load_dwordx2 v[30:31], v3, s[10:11] offset:512
	global_load_dwordx2 v[32:33], v3, s[10:11] offset:1024
	global_load_dwordx2 v[34:35], v3, s[10:11] offset:1536
	s_waitcnt vmcnt(16)
	v_lshlrev_b32_e32 v64, 16, v36
	v_and_b32_e32 v65, 0xffff0000, v36
	v_lshlrev_b32_e32 v66, 16, v37
	v_and_b32_e32 v67, 0xffff0000, v37
	v_mul_f32_e32 v8, v65, v65
	v_mul_f32_e32 v9, v67, v67
	v_fmac_f32_e32 v8, v64, v64
	v_fmac_f32_e32 v9, v66, v66
	v_add_f32_e32 v17, v8, v9
	v_lshlrev_b32_e32 v68, 16, v38
	v_and_b32_e32 v69, 0xffff0000, v38
	v_lshlrev_b32_e32 v70, 16, v39
	v_and_b32_e32 v71, 0xffff0000, v39
	v_mul_f32_e32 v8, v69, v69
	v_mul_f32_e32 v9, v71, v71
	v_fmac_f32_e32 v8, v68, v68
	v_fmac_f32_e32 v9, v70, v70
	v_add_f32_e32 v8, v8, v9
	v_add_f32_e32 v17, v17, v8
	v_lshlrev_b32_e32 v72, 16, v40
	v_and_b32_e32 v73, 0xffff0000, v40
	v_lshlrev_b32_e32 v74, 16, v41
	v_and_b32_e32 v75, 0xffff0000, v41
	v_mul_f32_e32 v8, v73, v73
	v_mul_f32_e32 v9, v75, v75
	v_fmac_f32_e32 v8, v72, v72
	v_fmac_f32_e32 v9, v74, v74
	v_add_f32_e32 v8, v8, v9
	v_add_f32_e32 v17, v17, v8
	v_lshlrev_b32_e32 v76, 16, v42
	v_and_b32_e32 v77, 0xffff0000, v42
	v_lshlrev_b32_e32 v78, 16, v43
	v_and_b32_e32 v79, 0xffff0000, v43
	v_mul_f32_e32 v8, v77, v77
	v_mul_f32_e32 v9, v79, v79
	v_fmac_f32_e32 v8, v76, v76
	v_fmac_f32_e32 v9, v78, v78
	v_add_f32_e32 v8, v8, v9
	v_add_f32_e32 v17, v17, v8
	v_lshlrev_b32_e32 v80, 16, v44
	v_and_b32_e32 v81, 0xffff0000, v44
	v_lshlrev_b32_e32 v82, 16, v45
	v_and_b32_e32 v83, 0xffff0000, v45
	v_mul_f32_e32 v8, v81, v81
	v_mul_f32_e32 v9, v83, v83
	v_fmac_f32_e32 v8, v80, v80
	v_fmac_f32_e32 v9, v82, v82
	v_add_f32_e32 v8, v8, v9
	v_add_f32_e32 v17, v17, v8
	v_lshlrev_b32_e32 v84, 16, v46
	v_and_b32_e32 v85, 0xffff0000, v46
	v_lshlrev_b32_e32 v86, 16, v47
	v_and_b32_e32 v87, 0xffff0000, v47
	v_mul_f32_e32 v8, v85, v85
	v_mul_f32_e32 v9, v87, v87
	v_fmac_f32_e32 v8, v84, v84
	v_fmac_f32_e32 v9, v86, v86
	v_add_f32_e32 v8, v8, v9
	v_add_f32_e32 v17, v17, v8
	v_lshlrev_b32_e32 v88, 16, v48
	v_and_b32_e32 v89, 0xffff0000, v48
	v_lshlrev_b32_e32 v90, 16, v49
	v_and_b32_e32 v91, 0xffff0000, v49
	v_mul_f32_e32 v8, v89, v89
	v_mul_f32_e32 v9, v91, v91
	v_fmac_f32_e32 v8, v88, v88
	v_fmac_f32_e32 v9, v90, v90
	v_add_f32_e32 v8, v8, v9
	v_add_f32_e32 v17, v17, v8
	v_lshlrev_b32_e32 v92, 16, v50
	v_and_b32_e32 v93, 0xffff0000, v50
	v_lshlrev_b32_e32 v94, 16, v51
	v_and_b32_e32 v95, 0xffff0000, v51
	v_mul_f32_e32 v8, v93, v93
	v_mul_f32_e32 v9, v95, v95
	v_fmac_f32_e32 v8, v92, v92
	v_fmac_f32_e32 v9, v94, v94
	v_add_f32_e32 v8, v8, v9
	v_add_f32_e32 v17, v17, v8
	ds_bpermute_b32 v18, v10, v17
	s_waitcnt lgkmcnt(0)
; __device__ __forceinline__ void final_norm_pass(const Ctx& C, const bf16* XB, const float* g, float* out) {
;     const int gw = C.bid * 8 + C.wave, NGW = C.G * 8;
;     for (int m = gw; m < M; m += NGW) {
;         const v2u* xr = (const v2u*)(XB + (size_t)m * D) + C.lane; f32x4 v[8]; float s = 0.f;
; #pragma unroll
;         for (int j = 0; j < 8; ++j) { const v2u w = xr[64 * j]; v[j] = (f32x4){__uint_as_float(w.x << 16), __uint_as_float(w.x & 0xffff0000u), __uint_as_float(w.y << 16), __uint_as_float(w.y & 0xffff0000u)};
;             s += (v[j][0] * v[j][0] + v[j][1] * v[j][1]) + (v[j][2] * v[j][2] + v[j][3] * v[j][3]); }
;         const float rstd = rsqrtf(wave_sum(s) * (1.0f / D) + EPS);
;         const f32x4* gr = (const f32x4*)g + C.lane; f32x4* o = (f32x4*)(out + (size_t)m * D) + C.lane;
; #pragma unroll
;         for (int j = 0; j < 8; ++j) o[64 * j] = v[j] * rstd * gr[64 * j];
;     }
	v_add_f32_e32 v17, v17, v18
	ds_bpermute_b32 v18, v11, v17
	s_waitcnt lgkmcnt(0)
	v_add_f32_e32 v17, v17, v18
	ds_bpermute_b32 v18, v12, v17
	s_waitcnt lgkmcnt(0)
	v_add_f32_e32 v17, v17, v18
	ds_bpermute_b32 v18, v13, v17
	s_waitcnt lgkmcnt(0)
	v_add_f32_e32 v17, v17, v18
	ds_bpermute_b32 v18, v14, v17
	s_waitcnt lgkmcnt(0)
	v_add_f32_e32 v17, v17, v18
	ds_bpermute_b32 v18, v15, v17
	s_waitcnt lgkmcnt(0)
	v_add_f32_e32 v17, v17, v18
	v_fmamk_f32 v6, v17, 0x3a000000, v5
	v_rsq_f32_e32 v6, v6
	s_nop 0
	v_pk_mul_f32 v[64:65], v[6:7], v[64:65] op_sel_hi:[0,1]
	v_pk_mul_f32 v[66:67], v[6:7], v[66:67] op_sel_hi:[0,1]
	v_pk_mul_f32 v[96:97], v[128:129], v[64:65]
	v_pk_mul_f32 v[98:99], v[130:131], v[66:67]
	global_store_dwordx4 v2, v[96:99], s[14:15] offset:-4096
	v_pk_mul_f32 v[68:69], v[6:7], v[68:69] op_sel_hi:[0,1]
	v_pk_mul_f32 v[70:71], v[6:7], v[70:71] op_sel_hi:[0,1]
	v_pk_mul_f32 v[100:101], v[132:133], v[68:69]
	v_pk_mul_f32 v[102:103], v[134:135], v[70:71]
	global_store_dwordx4 v2, v[100:103], s[14:15] offset:-3072
	v_pk_mul_f32 v[72:73], v[6:7], v[72:73] op_sel_hi:[0,1]
	v_pk_mul_f32 v[74:75], v[6:7], v[74:75] op_sel_hi:[0,1]
	v_pk_mul_f32 v[104:105], v[136:137], v[72:73]
	v_pk_mul_f32 v[106:107], v[138:139], v[74:75]
	global_store_dwordx4 v2, v[104:107], s[14:15] offset:-2048
	v_pk_mul_f32 v[76:77], v[6:7], v[76:77] op_sel_hi:[0,1]
	v_pk_mul_f32 v[78:79], v[6:7], v[78:79] op_sel_hi:[0,1]
	v_pk_mul_f32 v[108:109], v[140:141], v[76:77]
	v_pk_mul_f32 v[110:111], v[142:143], v[78:79]
	global_store_dwordx4 v2, v[108:111], s[14:15] offset:-1024
	v_pk_mul_f32 v[80:81], v[6:7], v[80:81] op_sel_hi:[0,1]
	v_pk_mul_f32 v[82:83], v[6:7], v[82:83] op_sel_hi:[0,1]
	v_pk_mul_f32 v[112:113], v[144:145], v[80:81]
	v_pk_mul_f32 v[114:115], v[146:147], v[82:83]
	global_store_dwordx4 v2, v[112:115], s[14:15] offset:0
	v_pk_mul_f32 v[84:85], v[6:7], v[84:85] op_sel_hi:[0,1]
	v_pk_mul_f32 v[86:87], v[6:7], v[86:87] op_sel_hi:[0,1]
	v_pk_mul_f32 v[116:117], v[148:149], v[84:85]
	v_pk_mul_f32 v[118:119], v[150:151], v[86:87]
	global_store_dwordx4 v2, v[116:119], s[14:15] offset:1024
	v_pk_mul_f32 v[88:89], v[6:7], v[88:89] op_sel_hi:[0,1]
	v_pk_mul_f32 v[90:91], v[6:7], v[90:91] op_sel_hi:[0,1]
	v_pk_mul_f32 v[120:121], v[152:153], v[88:89]
	v_pk_mul_f32 v[122:123], v[154:155], v[90:91]
	global_store_dwordx4 v2, v[120:123], s[14:15] offset:2048
	v_pk_mul_f32 v[92:93], v[6:7], v[92:93] op_sel_hi:[0,1]
	v_pk_mul_f32 v[94:95], v[6:7], v[94:95] op_sel_hi:[0,1]
	v_pk_mul_f32 v[124:125], v[156:157], v[92:93]
	v_pk_mul_f32 v[126:127], v[158:159], v[94:95]
	global_store_dwordx4 v2, v[124:127], s[14:15] offset:3072
	s_lshl_b32 s8, s2, 13
	s_add_u32 s14, s4, s8
	s_addc_u32 s15, s5, 0
	s_addk_i32 s2, 0x100
	s_lshl_b32 s8, s2, 12
	s_add_u32 s10, s6, s8
	s_addc_u32 s11, s7, 0
	global_load_dwordx2 v[36:37], v3, s[10:11] offset:-2048
	global_load_dwordx2 v[38:39], v3, s[10:11] offset:-1536
	global_load_dwordx2 v[40:41], v3, s[10:11] offset:-1024
	global_load_dwordx2 v[42:43], v3, s[10:11] offset:-512
	global_load_dwordx2 v[44:45], v3, s[10:11] offset:0
	global_load_dwordx2 v[46:47], v3, s[10:11] offset:512
	global_load_dwordx2 v[48:49], v3, s[10:11] offset:1024
	global_load_dwordx2 v[50:51], v3, s[10:11] offset:1536
	s_waitcnt vmcnt(16)
	v_lshlrev_b32_e32 v64, 16, v20
	v_and_b32_e32 v65, 0xffff0000, v20
	v_lshlrev_b32_e32 v66, 16, v21
	v_and_b32_e32 v67, 0xffff0000, v21
	v_mul_f32_e32 v8, v65, v65
	v_mul_f32_e32 v9, v67, v67
	v_fmac_f32_e32 v8, v64, v64
	v_fmac_f32_e32 v9, v66, v66
	v_add_f32_e32 v17, v8, v9
	v_lshlrev_b32_e32 v68, 16, v22
	v_and_b32_e32 v69, 0xffff0000, v22
	v_lshlrev_b32_e32 v70, 16, v23
	v_and_b32_e32 v71, 0xffff0000, v23
	v_mul_f32_e32 v8, v69, v69
	v_mul_f32_e32 v9, v71, v71
	v_fmac_f32_e32 v8, v68, v68
	v_fmac_f32_e32 v9, v70, v70
	v_add_f32_e32 v8, v8, v9
	v_add_f32_e32 v17, v17, v8
	v_lshlrev_b32_e32 v72, 16, v24
	v_and_b32_e32 v73, 0xffff0000, v24
	v_lshlrev_b32_e32 v74, 16, v25
	v_and_b32_e32 v75, 0xffff0000, v25
	v_mul_f32_e32 v8, v73, v73
	v_mul_f32_e32 v9, v75, v75
	v_fmac_f32_e32 v8, v72, v72
	v_fmac_f32_e32 v9, v74, v74
	v_add_f32_e32 v8, v8, v9
	v_add_f32_e32 v17, v17, v8
	v_lshlrev_b32_e32 v76, 16, v26
	v_and_b32_e32 v77, 0xffff0000, v26
	v_lshlrev_b32_e32 v78, 16, v27
	v_and_b32_e32 v79, 0xffff0000, v27
	v_mul_f32_e32 v8, v77, v77
	v_mul_f32_e32 v9, v79, v79
	v_fmac_f32_e32 v8, v76, v76
	v_fmac_f32_e32 v9, v78, v78
	v_add_f32_e32 v8, v8, v9
	v_add_f32_e32 v17, v17, v8
	v_lshlrev_b32_e32 v80, 16, v28
	v_and_b32_e32 v81, 0xffff0000, v28
	v_lshlrev_b32_e32 v82, 16, v29
	v_and_b32_e32 v83, 0xffff0000, v29
	v_mul_f32_e32 v8, v81, v81
	v_mul_f32_e32 v9, v83, v83
	v_fmac_f32_e32 v8, v80, v80
	v_fmac_f32_e32 v9, v82, v82
	v_add_f32_e32 v8, v8, v9
	v_add_f32_e32 v17, v17, v8
	v_lshlrev_b32_e32 v84, 16, v30
	v_and_b32_e32 v85, 0xffff0000, v30
	v_lshlrev_b32_e32 v86, 16, v31
	v_and_b32_e32 v87, 0xffff0000, v31
	v_mul_f32_e32 v8, v85, v85
	v_mul_f32_e32 v9, v87, v87
	v_fmac_f32_e32 v8, v84, v84
	v_fmac_f32_e32 v9, v86, v86
	v_add_f32_e32 v8, v8, v9
	v_add_f32_e32 v17, v17, v8
	v_lshlrev_b32_e32 v88, 16, v32
	v_and_b32_e32 v89, 0xffff0000, v32
	v_lshlrev_b32_e32 v90, 16, v33
	v_and_b32_e32 v91, 0xffff0000, v33
	v_mul_f32_e32 v8, v89, v89
	v_mul_f32_e32 v9, v91, v91
	v_fmac_f32_e32 v8, v88, v88
	v_fmac_f32_e32 v9, v90, v90
	v_add_f32_e32 v8, v8, v9
	v_add_f32_e32 v17, v17, v8
	v_lshlrev_b32_e32 v92, 16, v34
	v_and_b32_e32 v93, 0xffff0000, v34
	v_lshlrev_b32_e32 v94, 16, v35
	v_and_b32_e32 v95, 0xffff0000, v35
	v_mul_f32_e32 v8, v93, v93
	v_mul_f32_e32 v9, v95, v95
	v_fmac_f32_e32 v8, v92, v92
	v_fmac_f32_e32 v9, v94, v94
	v_add_f32_e32 v8, v8, v9
	v_add_f32_e32 v17, v17, v8
	ds_bpermute_b32 v18, v10, v17
	s_waitcnt lgkmcnt(0)
; __device__ __forceinline__ void final_norm_pass(const Ctx& C, const bf16* XB, const float* g, float* out) {
;     ...
;         const v2u* xr = (const v2u*)(XB + (size_t)m * D) + C.lane; f32x4 v[8]; float s = 0.f;
; #pragma unroll
;         for (int j = 0; j < 8; ++j) { const v2u w = xr[64 * j]; v[j] = (f32x4){__uint_as_float(w.x << 16), __uint_as_float(w.x & 0xffff0000u), __uint_as_float(w.y << 16), __uint_as_float(w.y & 0xffff0000u)};
;             s += (v[j][0] * v[j][0] + v[j][1] * v[j][1]) + (v[j][2] * v[j][2] + v[j][3] * v[j][3]); }
;         const float rstd = rsqrtf(wave_sum(s) * (1.0f / D) + EPS);
;         const f32x4* gr = (const f32x4*)g + C.lane; f32x4* o = (f32x4*)(out + (size_t)m * D) + C.lane;
; #pragma unroll
;         for (int j = 0; j < 8; ++j) o[64 * j] = v[j] * rstd * gr[64 * j];
	v_add_f32_e32 v17, v17, v18
	ds_bpermute_b32 v18, v11, v17
	s_waitcnt lgkmcnt(0)
	v_add_f32_e32 v17, v17, v18
	ds_bpermute_b32 v18, v12, v17
	s_waitcnt lgkmcnt(0)
	v_add_f32_e32 v17, v17, v18
	ds_bpermute_b32 v18, v13, v17
	s_waitcnt lgkmcnt(0)
	v_add_f32_e32 v17, v17, v18
	ds_bpermute_b32 v18, v14, v17
	s_waitcnt lgkmcnt(0)
	v_add_f32_e32 v17, v17, v18
	ds_bpermute_b32 v18, v15, v17
	s_waitcnt lgkmcnt(0)
	v_add_f32_e32 v17, v17, v18
	v_fmamk_f32 v6, v17, 0x3a000000, v5
	v_rsq_f32_e32 v6, v6
	s_nop 0
	v_pk_mul_f32 v[64:65], v[6:7], v[64:65] op_sel_hi:[0,1]
	v_pk_mul_f32 v[66:67], v[6:7], v[66:67] op_sel_hi:[0,1]
	v_pk_mul_f32 v[96:97], v[128:129], v[64:65]
	v_pk_mul_f32 v[98:99], v[130:131], v[66:67]
	global_store_dwordx4 v2, v[96:99], s[14:15] offset:-4096
	v_pk_mul_f32 v[68:69], v[6:7], v[68:69] op_sel_hi:[0,1]
	v_pk_mul_f32 v[70:71], v[6:7], v[70:71] op_sel_hi:[0,1]
	v_pk_mul_f32 v[100:101], v[132:133], v[68:69]
	v_pk_mul_f32 v[102:103], v[134:135], v[70:71]
	global_store_dwordx4 v2, v[100:103], s[14:15] offset:-3072
	v_pk_mul_f32 v[72:73], v[6:7], v[72:73] op_sel_hi:[0,1]
	v_pk_mul_f32 v[74:75], v[6:7], v[74:75] op_sel_hi:[0,1]
	v_pk_mul_f32 v[104:105], v[136:137], v[72:73]
	v_pk_mul_f32 v[106:107], v[138:139], v[74:75]
	global_store_dwordx4 v2, v[104:107], s[14:15] offset:-2048
	v_pk_mul_f32 v[76:77], v[6:7], v[76:77] op_sel_hi:[0,1]
	v_pk_mul_f32 v[78:79], v[6:7], v[78:79] op_sel_hi:[0,1]
	v_pk_mul_f32 v[108:109], v[140:141], v[76:77]
	v_pk_mul_f32 v[110:111], v[142:143], v[78:79]
	global_store_dwordx4 v2, v[108:111], s[14:15] offset:-1024
	v_pk_mul_f32 v[80:81], v[6:7], v[80:81] op_sel_hi:[0,1]
	v_pk_mul_f32 v[82:83], v[6:7], v[82:83] op_sel_hi:[0,1]
	v_pk_mul_f32 v[112:113], v[144:145], v[80:81]
	v_pk_mul_f32 v[114:115], v[146:147], v[82:83]
	global_store_dwordx4 v2, v[112:115], s[14:15] offset:0
	v_pk_mul_f32 v[84:85], v[6:7], v[84:85] op_sel_hi:[0,1]
	v_pk_mul_f32 v[86:87], v[6:7], v[86:87] op_sel_hi:[0,1]
	v_pk_mul_f32 v[116:117], v[148:149], v[84:85]
	v_pk_mul_f32 v[118:119], v[150:151], v[86:87]
	global_store_dwordx4 v2, v[116:119], s[14:15] offset:1024
	v_pk_mul_f32 v[88:89], v[6:7], v[88:89] op_sel_hi:[0,1]
	v_pk_mul_f32 v[90:91], v[6:7], v[90:91] op_sel_hi:[0,1]
	v_pk_mul_f32 v[120:121], v[152:153], v[88:89]
	v_pk_mul_f32 v[122:123], v[154:155], v[90:91]
	global_store_dwordx4 v2, v[120:123], s[14:15] offset:2048
	v_pk_mul_f32 v[92:93], v[6:7], v[92:93] op_sel_hi:[0,1]
	v_pk_mul_f32 v[94:95], v[6:7], v[94:95] op_sel_hi:[0,1]
	v_pk_mul_f32 v[124:125], v[156:157], v[92:93]
	v_pk_mul_f32 v[126:127], v[158:159], v[94:95]
	global_store_dwordx4 v2, v[124:127], s[14:15] offset:3072
	s_lshl_b32 s8, s2, 13
	s_add_u32 s14, s4, s8
	s_addc_u32 s15, s5, 0
	s_waitcnt vmcnt(8)
; __device__ __forceinline__ void final_norm_pass(const Ctx& C, const bf16* XB, const float* g, float* out) {
;     ...
;         const v2u* xr = (const v2u*)(XB + (size_t)m * D) + C.lane; f32x4 v[8]; float s = 0.f;
; #pragma unroll
;         for (int j = 0; j < 8; ++j) { const v2u w = xr[64 * j]; v[j] = (f32x4){__uint_as_float(w.x << 16), __uint_as_float(w.x & 0xffff0000u), __uint_as_float(w.y << 16), __uint_as_float(w.y & 0xffff0000u)};
;             s += (v[j][0] * v[j][0] + v[j][1] * v[j][1]) + (v[j][2] * v[j][2] + v[j][3] * v[j][3]); }
;         const float rstd = rsqrtf(wave_sum(s) * (1.0f / D) + EPS);
;         const f32x4* gr = (const f32x4*)g + C.lane; f32x4* o = (f32x4*)(out + (size_t)m * D) + C.lane;
; #pragma unroll
;         for (int j = 0; j < 8; ++j) o[64 * j] = v[j] * rstd * gr[64 * j];
	v_lshlrev_b32_e32 v64, 16, v36
	v_and_b32_e32 v65, 0xffff0000, v36
	v_lshlrev_b32_e32 v66, 16, v37
	v_and_b32_e32 v67, 0xffff0000, v37
	v_mul_f32_e32 v8, v65, v65
	v_mul_f32_e32 v9, v67, v67
	v_fmac_f32_e32 v8, v64, v64
	v_fmac_f32_e32 v9, v66, v66
	v_add_f32_e32 v17, v8, v9
	v_lshlrev_b32_e32 v68, 16, v38
	v_and_b32_e32 v69, 0xffff0000, v38
	v_lshlrev_b32_e32 v70, 16, v39
	v_and_b32_e32 v71, 0xffff0000, v39
	v_mul_f32_e32 v8, v69, v69
	v_mul_f32_e32 v9, v71, v71
	v_fmac_f32_e32 v8, v68, v68
	v_fmac_f32_e32 v9, v70, v70
	v_add_f32_e32 v8, v8, v9
	v_add_f32_e32 v17, v17, v8
	v_lshlrev_b32_e32 v72, 16, v40
	v_and_b32_e32 v73, 0xffff0000, v40
	v_lshlrev_b32_e32 v74, 16, v41
	v_and_b32_e32 v75, 0xffff0000, v41
	v_mul_f32_e32 v8, v73, v73
	v_mul_f32_e32 v9, v75, v75
	v_fmac_f32_e32 v8, v72, v72
	v_fmac_f32_e32 v9, v74, v74
	v_add_f32_e32 v8, v8, v9
	v_add_f32_e32 v17, v17, v8
	v_lshlrev_b32_e32 v76, 16, v42
	v_and_b32_e32 v77, 0xffff0000, v42
	v_lshlrev_b32_e32 v78, 16, v43
	v_and_b32_e32 v79, 0xffff0000, v43
	v_mul_f32_e32 v8, v77, v77
	v_mul_f32_e32 v9, v79, v79
	v_fmac_f32_e32 v8, v76, v76
	v_fmac_f32_e32 v9, v78, v78
	v_add_f32_e32 v8, v8, v9
	v_add_f32_e32 v17, v17, v8
	v_lshlrev_b32_e32 v80, 16, v44
	v_and_b32_e32 v81, 0xffff0000, v44
	v_lshlrev_b32_e32 v82, 16, v45
	v_and_b32_e32 v83, 0xffff0000, v45
	v_mul_f32_e32 v8, v81, v81
	v_mul_f32_e32 v9, v83, v83
	v_fmac_f32_e32 v8, v80, v80
	v_fmac_f32_e32 v9, v82, v82
	v_add_f32_e32 v8, v8, v9
	v_add_f32_e32 v17, v17, v8
	v_lshlrev_b32_e32 v84, 16, v46
	v_and_b32_e32 v85, 0xffff0000, v46
	v_lshlrev_b32_e32 v86, 16, v47
	v_and_b32_e32 v87, 0xffff0000, v47
	v_mul_f32_e32 v8, v85, v85
	v_mul_f32_e32 v9, v87, v87
	v_fmac_f32_e32 v8, v84, v84
	v_fmac_f32_e32 v9, v86, v86
	v_add_f32_e32 v8, v8, v9
	v_add_f32_e32 v17, v17, v8
	v_lshlrev_b32_e32 v88, 16, v48
	v_and_b32_e32 v89, 0xffff0000, v48
	v_lshlrev_b32_e32 v90, 16, v49
	v_and_b32_e32 v91, 0xffff0000, v49
	v_mul_f32_e32 v8, v89, v89
	v_mul_f32_e32 v9, v91, v91
	v_fmac_f32_e32 v8, v88, v88
	v_fmac_f32_e32 v9, v90, v90
	v_add_f32_e32 v8, v8, v9
	v_add_f32_e32 v17, v17, v8
	v_lshlrev_b32_e32 v92, 16, v50
	v_and_b32_e32 v93, 0xffff0000, v50
	v_lshlrev_b32_e32 v94, 16, v51
	v_and_b32_e32 v95, 0xffff0000, v51
	v_mul_f32_e32 v8, v93, v93
	v_mul_f32_e32 v9, v95, v95
	v_fmac_f32_e32 v8, v92, v92
	v_fmac_f32_e32 v9, v94, v94
	v_add_f32_e32 v8, v8, v9
	v_add_f32_e32 v17, v17, v8
	ds_bpermute_b32 v18, v10, v17
	s_waitcnt lgkmcnt(0)
	v_add_f32_e32 v17, v17, v18
	ds_bpermute_b32 v18, v11, v17
	s_waitcnt lgkmcnt(0)
	v_add_f32_e32 v17, v17, v18
	ds_bpermute_b32 v18, v12, v17
	s_waitcnt lgkmcnt(0)
	v_add_f32_e32 v17, v17, v18
	ds_bpermute_b32 v18, v13, v17
	s_waitcnt lgkmcnt(0)
	v_add_f32_e32 v17, v17, v18
	ds_bpermute_b32 v18, v14, v17
	s_waitcnt lgkmcnt(0)
	v_add_f32_e32 v17, v17, v18
	ds_bpermute_b32 v18, v15, v17
	s_waitcnt lgkmcnt(0)
	v_add_f32_e32 v17, v17, v18
	v_fmamk_f32 v6, v17, 0x3a000000, v5
	v_rsq_f32_e32 v6, v6
	s_nop 0
	v_pk_mul_f32 v[64:65], v[6:7], v[64:65] op_sel_hi:[0,1]
	v_pk_mul_f32 v[66:67], v[6:7], v[66:67] op_sel_hi:[0,1]
	v_pk_mul_f32 v[96:97], v[128:129], v[64:65]
	v_pk_mul_f32 v[98:99], v[130:131], v[66:67]
	global_store_dwordx4 v2, v[96:99], s[14:15] offset:-4096
	v_pk_mul_f32 v[68:69], v[6:7], v[68:69] op_sel_hi:[0,1]
	v_pk_mul_f32 v[70:71], v[6:7], v[70:71] op_sel_hi:[0,1]
	v_pk_mul_f32 v[100:101], v[132:133], v[68:69]
	v_pk_mul_f32 v[102:103], v[134:135], v[70:71]
	global_store_dwordx4 v2, v[100:103], s[14:15] offset:-3072
	v_pk_mul_f32 v[72:73], v[6:7], v[72:73] op_sel_hi:[0,1]
	v_pk_mul_f32 v[74:75], v[6:7], v[74:75] op_sel_hi:[0,1]
	v_pk_mul_f32 v[104:105], v[136:137], v[72:73]
	v_pk_mul_f32 v[106:107], v[138:139], v[74:75]
	global_store_dwordx4 v2, v[104:107], s[14:15] offset:-2048
	v_pk_mul_f32 v[76:77], v[6:7], v[76:77] op_sel_hi:[0,1]
	v_pk_mul_f32 v[78:79], v[6:7], v[78:79] op_sel_hi:[0,1]
	v_pk_mul_f32 v[108:109], v[140:141], v[76:77]
	v_pk_mul_f32 v[110:111], v[142:143], v[78:79]
	global_store_dwordx4 v2, v[108:111], s[14:15] offset:-1024
	v_pk_mul_f32 v[80:81], v[6:7], v[80:81] op_sel_hi:[0,1]
	v_pk_mul_f32 v[82:83], v[6:7], v[82:83] op_sel_hi:[0,1]
	v_pk_mul_f32 v[112:113], v[144:145], v[80:81]
	v_pk_mul_f32 v[114:115], v[146:147], v[82:83]
	global_store_dwordx4 v2, v[112:115], s[14:15] offset:0
	v_pk_mul_f32 v[84:85], v[6:7], v[84:85] op_sel_hi:[0,1]
	v_pk_mul_f32 v[86:87], v[6:7], v[86:87] op_sel_hi:[0,1]
	v_pk_mul_f32 v[116:117], v[148:149], v[84:85]
	v_pk_mul_f32 v[118:119], v[150:151], v[86:87]
	global_store_dwordx4 v2, v[116:119], s[14:15] offset:1024
	v_pk_mul_f32 v[88:89], v[6:7], v[88:89] op_sel_hi:[0,1]
	v_pk_mul_f32 v[90:91], v[6:7], v[90:91] op_sel_hi:[0,1]
	v_pk_mul_f32 v[120:121], v[152:153], v[88:89]
	v_pk_mul_f32 v[122:123], v[154:155], v[90:91]
	global_store_dwordx4 v2, v[120:123], s[14:15] offset:2048
	v_pk_mul_f32 v[92:93], v[6:7], v[92:93] op_sel_hi:[0,1]
	v_pk_mul_f32 v[94:95], v[6:7], v[94:95] op_sel_hi:[0,1]
	v_pk_mul_f32 v[124:125], v[156:157], v[92:93]
	v_pk_mul_f32 v[126:127], v[158:159], v[94:95]
	global_store_dwordx4 v2, v[124:127], s[14:15] offset:3072
